# bonus scalar sum(r*k'*r_k) per (token,head) now produced by the scan's P1 waves into a 2 MB f32 array; group-norm phase reads it instead of re-reading r, k, a (-200 MB HBM traffic); attention q/z load
# speedup vs baseline: 1.0633x; 1.0325x over previous
; #define LAS __attribute__((address_space(3)))
; __device__ __forceinline__ void attn_phase(LAS unsigned char* lds, const bf16_t* QKVZ, const float* sinks, bf16_t* OG, int G, int bid, int tid) {
;     ...
;         const int g = wave >> 1, qh = wave & 1, h = kvh * 4 + g;
;         const float sink2 = sinks[h] * 1.4426950408889634f;
;         for (int mt = 0; mt < 4; ++mt) {
;             const int qo0 = qh * 64 + mt * 16;
;             const size_t row = (size_t)(b * T + n * 128 + qo0 + fr);
;             const bf16_t* qp = QKVZ + row * ATT_IN + h * 64 + fq * 8;
;             const bf16x8 q0 = *(const bf16x8*)qp, q1 = *(const bf16x8*)(qp + 32);
;             const int kt0 = (qh * 4 + mt) < 6 ? (qh * 4 + mt) : 6;
;             f32x4 s[10];
; #pragma unroll
;             for (int kt = 0; kt < 10; ++kt) {
;                 const LAS unsigned char* kp = Kl + ((kt0 + kt) * 16 + fr) * KP + fq * 16;
;                 const bf16x8 k0 = *(const LAS bf16x8*)kp, k1 = *(const LAS bf16x8*)(kp + 64);
;                 f32x4 acc = (f32x4){0.f, 0.f, 0.f, 0.f};
;                 acc = __builtin_amdgcn_mfma_f32_16x16x32_bf16(k0, q0, acc, 0, 0, 0);
;                 acc = __builtin_amdgcn_mfma_f32_16x16x32_bf16(k1, q1, acc, 0, 0, 0);
;                 s[kt] = acc;
.LBB0_245:
	s_lshl_b32 s1, s12, 2
	s_and_b32 s1, s1, 12
	s_bfe_u32 s0, s12, 0x50002
	s_add_i32 s12, s1, s17
	s_ashr_i32 s13, s12, 31
	s_and_b32 s8, s16, 0xfffff000
	s_lshl_b64 s[14:15], s[12:13], 2
	s_add_u32 s14, s6, s14
	s_addc_u32 s15, s7, s15
	s_waitcnt lgkmcnt(0)
	s_barrier
	global_load_dword v32, v73, s[14:15]
	s_lshl_b32 s14, s12, 6
	s_ashr_i32 s15, s14, 31
	s_cmp_lg_u32 s0, 0
	s_cselect_b64 s[12:13], -1, 0
	s_lshl_b64 s[14:15], s[14:15], 1
	v_or_b32_e32 v33, s8, v99
	v_lshl_add_u64 v[80:81], v[78:79], 0, s[14:15]
	s_add_u32 s14, s4, s14
	s_mov_b32 s1, 0
	v_mov_b32_e32 v139, v119
	v_lshl_or_b32 v140, s0, 7, v33
	s_addc_u32 s15, s5, s15
	s_mov_b32 s8, s18
	v_mov_b64_e32 v[194:195], s[14:15]
	v_mad_i64_i32 v[196:197], s[26:27], v140, s22, v[194:195]
	v_lshl_add_u64 v[194:195], v[196:197], 0, v[72:73]
	global_load_dwordx4 v[186:189], v[194:195], off
	global_load_dwordx4 v[190:193], v[194:195], off offset:64
	s_waitcnt vmcnt(0)
	v_mul_f32_e32 v141, 0x3fb8aa3b, v32
.LBB0_246:
	v_add_u32_e32 v82, s1, v140
	v_mov_b64_e32 v[32:33], s[14:15]
	v_mad_i64_i32 v[84:85], s[26:27], v82, s22, v[32:33]
	v_lshl_add_u64 v[36:37], v[84:85], 0, v[72:73]
	s_waitcnt vmcnt(4)
	v_mov_b64_e32 v[32:33], v[186:187]
	v_mov_b64_e32 v[34:35], v[188:189]
	v_mov_b64_e32 v[162:163], v[190:191]
	v_mov_b64_e32 v[164:165], v[192:193]
	v_add_co_u32_e32 v194, vcc, 0x14000, v36
	s_nop 1
	v_addc_co_u32_e32 v195, vcc, 0, v37, vcc
	global_load_dwordx4 v[186:189], v[194:195], off
	global_load_dwordx4 v[190:193], v[194:195], off offset:64
	v_lshlrev_b32_e32 v196, 1, v76
	v_mov_b32_e32 v197, v73
	v_lshl_add_u64 v[198:199], v[84:85], 0, v[196:197]
	global_load_dwordx2 v[200:201], v[198:199], off offset:3072
	global_load_dwordx2 v[202:203], v[198:199], off offset:3104
	global_load_dwordx2 v[204:205], v[198:199], off offset:3136
	global_load_dwordx2 v[206:207], v[198:199], off offset:3168
	s_min_u32 s25, s8, 6
	s_lshl_b32 s25, s25, 4
	v_or_b32_e32 v36, s25, v89
	v_mad_u32_u24 v40, v36, s19, v90
	ds_read_b128 v[36:39], v40
	ds_read_b128 v[40:43], v40 offset:64
	s_add_i32 s26, s25, 16
	s_add_i32 s29, s25, 32
	s_add_i32 s28, s25, 64
	s_add_i32 s27, s25, 0x60
	s_add_i32 s30, s25, 0x90
	v_subrev_u32_e32 v185, s25, v129
	v_add_u32_e32 v146, s25, v139
	v_subrev_u32_e32 v180, s25, v118
	v_subrev_u32_e32 v179, s25, v117
	v_subrev_u32_e32 v184, s25, v128
	v_subrev_u32_e32 v178, s25, v116
	v_subrev_u32_e32 v175, s25, v107
	v_subrev_u32_e32 v183, s25, v127
	v_subrev_u32_e32 v177, s25, v115
	v_subrev_u32_e32 v174, s25, v106
	v_subrev_u32_e32 v182, s25, v126
	v_subrev_u32_e32 v176, s25, v114
	v_subrev_u32_e32 v161, s25, v105
	v_subrev_u32_e32 v181, s25, v125
	v_subrev_u32_e32 v159, s25, v113
	v_subrev_u32_e32 v158, s25, v104
	v_subrev_u32_e32 v160, s25, v124
	v_subrev_u32_e32 v156, s25, v112
	v_subrev_u32_e32 v155, s25, v103
	v_subrev_u32_e32 v157, s25, v123
	v_subrev_u32_e32 v152, s25, v111
	v_subrev_u32_e32 v151, s25, v102
	v_subrev_u32_e32 v153, s25, v122
	v_subrev_u32_e32 v149, s25, v110
	v_subrev_u32_e32 v147, s25, v101
	v_subrev_u32_e32 v150, s25, v121
	v_subrev_u32_e32 v145, s25, v109
	v_subrev_u32_e32 v144, s25, v100
	v_subrev_u32_e32 v148, s25, v120
	v_subrev_u32_e32 v143, s25, v108
	v_subrev_u32_e32 v142, s25, v98
	v_ashrrev_i32_e32 v83, 31, v82
	v_add_u32_e32 v139, -16, v139
	s_waitcnt lgkmcnt(1)
	v_mfma_f32_16x16x32_bf16 v[36:39], v[36:39], v[32:35], 0
	s_waitcnt lgkmcnt(0)
	v_mfma_f32_16x16x32_bf16 v[68:71], v[40:43], v[162:165], v[36:39]
	s_nop 5
	v_or_b32_e32 v36, s26, v89
	v_mad_u32_u24 v40, v36, s19, v90
	ds_read_b128 v[36:39], v40
	ds_read_b128 v[40:43], v40 offset:64
	s_waitcnt lgkmcnt(1)
	v_mfma_f32_16x16x32_bf16 v[36:39], v[36:39], v[32:35], 0
	s_add_i32 s26, s25, 48
	s_waitcnt lgkmcnt(0)
	v_mfma_f32_16x16x32_bf16 v[64:67], v[40:43], v[162:165], v[36:39]
	s_nop 4
	v_or_b32_e32 v36, s29, v89
	v_mad_u32_u24 v40, v36, s19, v90
	ds_read_b128 v[36:39], v40
	ds_read_b128 v[40:43], v40 offset:64
	s_waitcnt lgkmcnt(1)
	v_mfma_f32_16x16x32_bf16 v[36:39], v[36:39], v[32:35], 0
	s_waitcnt lgkmcnt(0)
	v_mfma_f32_16x16x32_bf16 v[60:63], v[40:43], v[162:165], v[36:39]
	s_nop 5
	v_or_b32_e32 v36, s26, v89
	v_mad_u32_u24 v40, v36, s19, v90
	ds_read_b128 v[36:39], v40
	ds_read_b128 v[40:43], v40 offset:64
	s_waitcnt lgkmcnt(1)
	v_mfma_f32_16x16x32_bf16 v[36:39], v[36:39], v[32:35], 0
	s_add_i32 s26, s25, 0x50
	s_waitcnt lgkmcnt(0)
	v_mfma_f32_16x16x32_bf16 v[56:59], v[40:43], v[162:165], v[36:39]
	s_nop 4
	v_or_b32_e32 v36, s28, v89
	v_mad_u32_u24 v40, v36, s19, v90
	ds_read_b128 v[36:39], v40
	ds_read_b128 v[40:43], v40 offset:64
	s_waitcnt lgkmcnt(1)
	v_mfma_f32_16x16x32_bf16 v[36:39], v[36:39], v[32:35], 0
	s_waitcnt lgkmcnt(0)
	v_mfma_f32_16x16x32_bf16 v[52:55], v[40:43], v[162:165], v[36:39]
	s_nop 5
	v_or_b32_e32 v36, s26, v89
	v_mad_u32_u24 v40, v36, s19, v90
	ds_read_b128 v[36:39], v40
	ds_read_b128 v[40:43], v40 offset:64
	s_waitcnt lgkmcnt(1)
	v_mfma_f32_16x16x32_bf16 v[36:39], v[36:39], v[32:35], 0
	s_add_i32 s26, s25, 0x70
	s_waitcnt lgkmcnt(0)
	v_mfma_f32_16x16x32_bf16 v[48:51], v[40:43], v[162:165], v[36:39]
	s_nop 4
	v_or_b32_e32 v36, s27, v89
	v_mad_u32_u24 v40, v36, s19, v90
	ds_read_b128 v[36:39], v40
	ds_read_b128 v[40:43], v40 offset:64
	s_waitcnt lgkmcnt(1)
	v_mfma_f32_16x16x32_bf16 v[36:39], v[36:39], v[32:35], 0
	s_waitcnt lgkmcnt(0)
	v_mfma_f32_16x16x32_bf16 v[44:47], v[40:43], v[162:165], v[36:39]
	s_nop 5
	v_or_b32_e32 v36, s26, v89
	v_mad_u32_u24 v40, v36, s19, v90
	ds_read_b128 v[36:39], v40
	ds_read_b128 v[40:43], v40 offset:64
	s_waitcnt lgkmcnt(1)
	v_mfma_f32_16x16x32_bf16 v[36:39], v[36:39], v[32:35], 0
	s_or_b32 s26, s25, 0x80
	s_waitcnt lgkmcnt(0)
; #define LAS __attribute__((address_space(3)))
; __device__ __forceinline__ void attn_phase(LAS unsigned char* lds, const bf16_t* QKVZ, const float* sinks, bf16_t* OG, int G, int bid, int tid) {
;     ...
;             for (int kt = 0; kt < 10; ++kt) {
;                 const LAS unsigned char* kp = Kl + ((kt0 + kt) * 16 + fr) * KP + fq * 16;
;                 const bf16x8 k0 = *(const LAS bf16x8*)kp, k1 = *(const LAS bf16x8*)(kp + 64);
;                 f32x4 acc = (f32x4){0.f, 0.f, 0.f, 0.f};
;                 acc = __builtin_amdgcn_mfma_f32_16x16x32_bf16(k0, q0, acc, 0, 0, 0);
;                 acc = __builtin_amdgcn_mfma_f32_16x16x32_bf16(k1, q1, acc, 0, 0, 0);
;                 s[kt] = acc;
;             }
;             const int qi = 128 + qo0 + fr;
;             float mx = sink2;
; #pragma unroll
;             for (int kt = 0; kt < 10; ++kt)
; #pragma unroll
;                 for (int r = 0; r < 4; ++r) { const int si = (kt0 + kt) * 16 + 4 * fq + r, df = qi - si; const bool ok = (df >= 0) && (df < 128) && (n > 0 || si >= 128);
;                     const float v = ok ? s[kt][r] : -1e30f; s[kt][r] = v; mx = fmaxf(mx, v); }
	v_mfma_f32_16x16x32_bf16 v[40:43], v[40:43], v[162:165], v[36:39]
	s_nop 4
	v_or_b32_e32 v36, s26, v89
	v_mad_u32_u24 v154, v36, s19, v90
	ds_read_b128 v[36:39], v154
	ds_read_b128 v[166:169], v154 offset:64
	s_waitcnt lgkmcnt(1)
	v_mfma_f32_16x16x32_bf16 v[36:39], v[36:39], v[32:35], 0
	v_or_b32_e32 v154, s30, v89
	v_mad_u32_u24 v154, v154, s19, v90
	s_waitcnt lgkmcnt(0)
	v_mfma_f32_16x16x32_bf16 v[36:39], v[166:169], v[162:165], v[36:39]
	ds_read_b128 v[166:169], v154
	ds_read_b128 v[170:173], v154 offset:64
	v_or_b32_e32 v154, s25, v76
	s_waitcnt lgkmcnt(1)
	v_mfma_f32_16x16x32_bf16 v[32:35], v[166:169], v[32:35], 0
	s_waitcnt lgkmcnt(0)
	v_mfma_f32_16x16x32_bf16 v[32:35], v[170:173], v[162:165], v[32:35]
	v_add_u32_e32 v162, s1, v99
	v_add_u32_e32 v163, v162, v185
	v_cmp_gt_u32_e32 vcc, s20, v163
	s_and_b64 vcc, s[12:13], vcc
	v_add_u32_e32 v163, 0xffffff80, v146
	v_cndmask_b32_e32 v68, v138, v68, vcc
	v_cmp_lt_u32_e32 vcc, s23, v163
	s_and_b64 vcc, s[12:13], vcc
	v_add_u32_e32 v164, v162, v180
	v_cndmask_b32_e32 v69, v138, v69, vcc
	v_cmp_gt_u32_e32 vcc, s20, v164
	s_and_b64 vcc, s[12:13], vcc
	v_add_u32_e32 v164, v162, v179
	v_cndmask_b32_e32 v70, v138, v70, vcc
	v_cmp_gt_u32_e32 vcc, s20, v164
	s_and_b64 vcc, s[12:13], vcc
	v_add_u32_e32 v164, v162, v184
	v_cndmask_b32_e32 v71, v138, v71, vcc
	v_cmp_gt_u32_e32 vcc, s20, v164
	s_and_b64 vcc, s[12:13], vcc
	v_add_u32_e32 v164, 0xffffff90, v146
	v_cndmask_b32_e32 v64, v138, v64, vcc
	v_cmp_lt_u32_e32 vcc, s23, v164
	s_and_b64 vcc, s[12:13], vcc
	v_add_u32_e32 v164, v162, v178
	v_cndmask_b32_e32 v65, v138, v65, vcc
	v_cmp_gt_u32_e32 vcc, s20, v164
	s_and_b64 vcc, s[12:13], vcc
	v_add_u32_e32 v164, v162, v175
	v_cndmask_b32_e32 v66, v138, v66, vcc
	v_cmp_gt_u32_e32 vcc, s20, v164
	s_and_b64 vcc, s[12:13], vcc
	s_cmp_gt_u32 s8, 5
	v_add_u32_e32 v165, v162, v183
	s_cselect_b64 s[30:31], -1, 0
	v_cndmask_b32_e32 v67, v138, v67, vcc
	v_cmp_gt_u32_e32 vcc, s20, v165
	s_or_b64 s[30:31], s[12:13], s[30:31]
	s_and_b64 vcc, vcc, s[30:31]
	v_add_u32_e32 v165, 0xffffffa0, v146
	v_cndmask_b32_e32 v60, v138, v60, vcc
	v_cmp_lt_u32_e32 vcc, s23, v165
	s_and_b64 vcc, vcc, s[30:31]
	v_add_u32_e32 v165, v162, v177
	v_cndmask_b32_e32 v61, v138, v61, vcc
	v_cmp_gt_u32_e32 vcc, s20, v165
	s_and_b64 vcc, vcc, s[30:31]
	v_add_u32_e32 v165, v162, v174
	v_cndmask_b32_e32 v62, v138, v62, vcc
	v_cmp_gt_u32_e32 vcc, s20, v165
	s_and_b64 vcc, vcc, s[30:31]
	s_cmp_gt_u32 s8, 4
	v_add_u32_e32 v165, v162, v182
	s_cselect_b64 s[30:31], -1, 0
	v_cndmask_b32_e32 v63, v138, v63, vcc
	v_cmp_gt_u32_e32 vcc, s20, v165
	s_or_b64 s[30:31], s[12:13], s[30:31]
	s_and_b64 vcc, vcc, s[30:31]
	v_add_u32_e32 v165, 0xffffffb0, v146
	v_cndmask_b32_e32 v56, v138, v56, vcc
	v_cmp_lt_u32_e32 vcc, s23, v165
	s_and_b64 vcc, vcc, s[30:31]
	v_add_u32_e32 v165, v162, v176
	v_cndmask_b32_e32 v57, v138, v57, vcc
	v_cmp_gt_u32_e32 vcc, s20, v165
	s_and_b64 vcc, vcc, s[30:31]
	v_add_u32_e32 v161, v162, v161
	v_cndmask_b32_e32 v58, v138, v58, vcc
	v_cmp_gt_u32_e32 vcc, s20, v161
	s_and_b64 vcc, vcc, s[30:31]
	s_cmp_gt_u32 s8, 3
	v_add_u32_e32 v165, v162, v181
	s_cselect_b64 s[30:31], -1, 0
	v_cndmask_b32_e32 v59, v138, v59, vcc
	v_cmp_gt_u32_e32 vcc, s20, v165
	s_or_b64 s[30:31], s[12:13], s[30:31]
	s_and_b64 vcc, vcc, s[30:31]
	v_subrev_u32_e32 v165, 64, v146
	v_cndmask_b32_e32 v52, v138, v52, vcc
	v_cmp_lt_u32_e32 vcc, s23, v165
	s_and_b64 vcc, vcc, s[30:31]
	v_add_u32_e32 v159, v162, v159
	v_cndmask_b32_e32 v53, v138, v53, vcc
	v_cmp_gt_u32_e32 vcc, s20, v159
	s_and_b64 vcc, vcc, s[30:31]
	v_add_u32_e32 v158, v162, v158
	v_cndmask_b32_e32 v54, v138, v54, vcc
	v_cmp_gt_u32_e32 vcc, s20, v158
	s_and_b64 vcc, vcc, s[30:31]
	s_cmp_gt_u32 s8, 2
	v_add_u32_e32 v159, v162, v160
	s_cselect_b64 s[30:31], -1, 0
	v_cndmask_b32_e32 v55, v138, v55, vcc
	v_cmp_gt_u32_e32 vcc, s20, v159
	s_or_b64 s[30:31], s[12:13], s[30:31]
	s_and_b64 vcc, vcc, s[30:31]
	v_subrev_u32_e32 v159, 48, v146
	v_cndmask_b32_e32 v48, v138, v48, vcc
	v_cmp_lt_u32_e32 vcc, s23, v159
	s_and_b64 vcc, vcc, s[30:31]
	v_add_u32_e32 v156, v162, v156
	v_cndmask_b32_e32 v49, v138, v49, vcc
	v_cmp_gt_u32_e32 vcc, s20, v156
	s_and_b64 vcc, vcc, s[30:31]
	v_add_u32_e32 v155, v162, v155
	v_cndmask_b32_e32 v50, v138, v50, vcc
	v_cmp_gt_u32_e32 vcc, s20, v155
	s_and_b64 vcc, vcc, s[30:31]
	s_cmp_gt_u32 s8, 1
	v_add_u32_e32 v157, v162, v157
	s_cselect_b64 s[30:31], -1, 0
	v_cndmask_b32_e32 v51, v138, v51, vcc
	v_cmp_gt_u32_e32 vcc, s20, v157
	s_or_b64 s[30:31], s[12:13], s[30:31]
	s_and_b64 vcc, vcc, s[30:31]
	v_subrev_u32_e32 v157, 32, v146
	v_cndmask_b32_e32 v44, v138, v44, vcc
	v_cmp_lt_u32_e32 vcc, s23, v157
	s_and_b64 vcc, vcc, s[30:31]
	v_add_u32_e32 v152, v162, v152
	v_cndmask_b32_e32 v45, v138, v45, vcc
	v_cmp_gt_u32_e32 vcc, s20, v152
	s_and_b64 vcc, vcc, s[30:31]
	v_add_u32_e32 v151, v162, v151
	v_cndmask_b32_e32 v46, v138, v46, vcc
	v_cmp_gt_u32_e32 vcc, s20, v151
	v_max3_f32 v163, v141, v68, v69
	s_and_b64 vcc, vcc, s[30:31]
	s_or_b32 s30, s8, s0
	v_max3_f32 v163, v163, v70, v71
	v_add_u32_e32 v152, v162, v153
	s_cmp_lg_u32 s30, 0
	v_max3_f32 v163, v163, v64, v65
	v_cndmask_b32_e32 v47, v138, v47, vcc
	v_cmp_gt_u32_e32 vcc, s20, v152
	s_cselect_b64 s[30:31], -1, 0
	v_max3_f32 v163, v163, v66, v67
	s_and_b64 vcc, s[30:31], vcc
	v_add_u32_e32 v152, -16, v146
	v_max3_f32 v163, v163, v60, v61
	v_cndmask_b32_e32 v40, v138, v40, vcc
	v_cmp_lt_u32_e32 vcc, s23, v152
	v_max3_f32 v163, v163, v62, v63
	s_and_b64 vcc, s[30:31], vcc
	v_add_u32_e32 v149, v162, v149
	v_max3_f32 v163, v163, v56, v57
	v_cndmask_b32_e32 v41, v138, v41, vcc
	v_cmp_gt_u32_e32 vcc, s20, v149
	v_max3_f32 v161, v163, v58, v59
; __device__ __forceinline__ void attn_phase(LAS unsigned char* lds, const bf16_t* QKVZ, const float* sinks, bf16_t* OG, int G, int bid, int tid) {
;     ...
;                     const float v = ok ? s[kt][r] : -1e30f; s[kt][r] = v; mx = fmaxf(mx, v); }
;             mx = fmaxf(mx, __shfl_xor(mx, 16)); mx = fmaxf(mx, __shfl_xor(mx, 32));
;             float sum = 0.f;
; #pragma unroll
;             for (int kt = 0; kt < 10; ++kt)
; #pragma unroll
;                 for (int r = 0; r < 4; ++r) { const float p = __builtin_amdgcn_exp2f(s[kt][r] - mx); s[kt][r] = p; sum += p; }
;             sum += __shfl_xor(sum, 16); sum += __shfl_xor(sum, 32);
	s_and_b64 vcc, s[30:31], vcc
	v_add_u32_e32 v147, v162, v147
	v_max3_f32 v161, v161, v52, v53
	v_cndmask_b32_e32 v42, v138, v42, vcc
	v_cmp_gt_u32_e32 vcc, s20, v147
	v_max3_f32 v158, v161, v54, v55
	s_and_b64 vcc, s[30:31], vcc
	v_add_u32_e32 v150, v162, v150
	v_max3_f32 v158, v158, v48, v49
	v_cndmask_b32_e32 v43, v138, v43, vcc
	v_cmp_gt_u32_e32 vcc, s20, v150
	v_max3_f32 v155, v158, v50, v51
	v_add_u32_e32 v145, v162, v145
	v_cndmask_b32_e32 v36, v138, v36, vcc
	v_cmp_lt_u32_e32 vcc, s23, v146
	v_max3_f32 v155, v155, v44, v45
	v_add_u32_e32 v144, v162, v144
	v_cndmask_b32_e32 v37, v138, v37, vcc
	v_cmp_gt_u32_e32 vcc, s20, v145
	v_max3_f32 v151, v155, v46, v47
	v_add_u32_e32 v145, v162, v148
	v_cndmask_b32_e32 v38, v138, v38, vcc
	v_cmp_gt_u32_e32 vcc, s20, v144
	v_max3_f32 v151, v151, v40, v41
	v_max3_f32 v147, v151, v42, v43
	v_cndmask_b32_e32 v39, v138, v39, vcc
	v_cmp_gt_u32_e32 vcc, s20, v145
	v_add_u32_e32 v145, 16, v146
	v_add_u32_e32 v143, v162, v143
	v_cndmask_b32_e32 v32, v138, v32, vcc
	v_cmp_lt_u32_e32 vcc, s23, v145
	v_max3_f32 v147, v147, v36, v37
	v_add_u32_e32 v142, v162, v142
	v_cndmask_b32_e32 v33, v138, v33, vcc
	v_cmp_gt_u32_e32 vcc, s20, v143
	v_max3_f32 v144, v147, v38, v39
	v_max3_f32 v144, v144, v32, v33
	v_cndmask_b32_e32 v34, v138, v34, vcc
	v_cmp_gt_u32_e32 vcc, s20, v142
	v_or_b32_e32 v164, s29, v76
	v_or_b32_e32 v163, s28, v76
	v_cndmask_b32_e32 v35, v138, v35, vcc
	v_max3_f32 v142, v144, v34, v35
	ds_bpermute_b32 v143, v91, v142
	v_or_b32_e32 v156, s27, v76
	v_or_b32_e32 v149, s26, v76
	s_add_i32 s1, s1, 16
	s_add_i32 s8, s8, 1
	s_waitcnt lgkmcnt(0)
	v_max_f32_e32 v143, v143, v143
	v_max_f32_e32 v142, v142, v143
	ds_bpermute_b32 v143, v92, v142
	s_cmp_eq_u32 s1, 64
	s_waitcnt lgkmcnt(0)
	v_max_f32_e32 v143, v143, v143
	v_max_f32_e32 v142, v142, v143
	v_sub_f32_e32 v68, v68, v142
	v_exp_f32_e32 v68, v68
	v_sub_f32_e32 v69, v69, v142
	v_exp_f32_e32 v69, v69
	v_sub_f32_e32 v70, v70, v142
	v_exp_f32_e32 v70, v70
	v_sub_f32_e32 v71, v71, v142
	v_exp_f32_e32 v71, v71
	v_sub_f32_e32 v64, v64, v142
	v_add_f32_e32 v143, 0, v68
	v_exp_f32_e32 v64, v64
	v_sub_f32_e32 v65, v65, v142
	v_add_f32_e32 v143, v69, v143
	v_exp_f32_e32 v65, v65
	v_sub_f32_e32 v66, v66, v142
	v_add_f32_e32 v143, v70, v143
	v_exp_f32_e32 v66, v66
	v_sub_f32_e32 v67, v67, v142
	v_add_f32_e32 v143, v71, v143
	v_exp_f32_e32 v67, v67
	v_sub_f32_e32 v60, v60, v142
	v_add_f32_e32 v143, v64, v143
	v_exp_f32_e32 v60, v60
	v_sub_f32_e32 v61, v61, v142
	v_add_f32_e32 v143, v65, v143
	v_exp_f32_e32 v61, v61
	v_sub_f32_e32 v62, v62, v142
	v_add_f32_e32 v143, v66, v143
	v_exp_f32_e32 v62, v62
	v_sub_f32_e32 v63, v63, v142
	v_add_f32_e32 v143, v67, v143
	v_exp_f32_e32 v63, v63
	v_sub_f32_e32 v56, v56, v142
	v_add_f32_e32 v143, v60, v143
	v_exp_f32_e32 v56, v56
	v_sub_f32_e32 v57, v57, v142
	v_add_f32_e32 v143, v61, v143
	v_exp_f32_e32 v57, v57
	v_sub_f32_e32 v58, v58, v142
	v_add_f32_e32 v143, v62, v143
	v_exp_f32_e32 v58, v58
	v_sub_f32_e32 v59, v59, v142
	v_add_f32_e32 v143, v63, v143
	v_exp_f32_e32 v59, v59
	v_sub_f32_e32 v52, v52, v142
	v_add_f32_e32 v143, v56, v143
	v_exp_f32_e32 v144, v52
	v_add_f32_e32 v143, v57, v143
	v_add_f32_e32 v143, v58, v143
	v_add_f32_e32 v143, v59, v143
	v_sub_f32_e32 v53, v53, v142
	v_add_f32_e32 v52, v144, v143
	v_exp_f32_e32 v143, v53
	v_sub_f32_e32 v53, v54, v142
	v_exp_f32_e32 v145, v53
	v_sub_f32_e32 v53, v55, v142
	v_exp_f32_e32 v146, v53
	v_sub_f32_e32 v48, v48, v142
	v_exp_f32_e32 v147, v48
	v_sub_f32_e32 v49, v49, v142
	v_add_f32_e32 v52, v143, v52
	v_exp_f32_e32 v148, v49
	v_sub_f32_e32 v49, v50, v142
	v_add_f32_e32 v52, v145, v52
	v_exp_f32_e32 v150, v49
	v_sub_f32_e32 v49, v51, v142
	v_add_f32_e32 v52, v146, v52
	v_exp_f32_e32 v151, v49
	v_sub_f32_e32 v44, v44, v142
	v_add_f32_e32 v48, v147, v52
	v_exp_f32_e32 v152, v44
	v_sub_f32_e32 v45, v45, v142
	v_add_f32_e32 v48, v148, v48
	v_exp_f32_e32 v153, v45
	v_sub_f32_e32 v45, v46, v142
	v_add_f32_e32 v48, v150, v48
	v_exp_f32_e32 v155, v45
	v_sub_f32_e32 v45, v47, v142
	v_add_f32_e32 v48, v151, v48
	v_exp_f32_e32 v157, v45
	v_sub_f32_e32 v40, v40, v142
	v_add_f32_e32 v44, v152, v48
	v_exp_f32_e32 v158, v40
	v_sub_f32_e32 v41, v41, v142
	v_add_f32_e32 v44, v153, v44
	v_exp_f32_e32 v159, v41
	v_sub_f32_e32 v41, v42, v142
	v_add_f32_e32 v44, v155, v44
	v_exp_f32_e32 v160, v41
	v_sub_f32_e32 v41, v43, v142
	v_add_f32_e32 v44, v157, v44
	v_exp_f32_e32 v161, v41
	v_sub_f32_e32 v36, v36, v142
	v_add_f32_e32 v40, v158, v44
	v_exp_f32_e32 v162, v36
	v_sub_f32_e32 v37, v37, v142
	v_add_f32_e32 v40, v159, v40
	v_exp_f32_e32 v165, v37
	v_sub_f32_e32 v37, v38, v142
	v_add_f32_e32 v40, v160, v40
	v_exp_f32_e32 v166, v37
	v_sub_f32_e32 v37, v39, v142
	v_add_f32_e32 v40, v161, v40
	v_exp_f32_e32 v167, v37
	v_sub_f32_e32 v32, v32, v142
	v_add_f32_e32 v36, v162, v40
	v_exp_f32_e32 v168, v32
	v_sub_f32_e32 v33, v33, v142
	v_add_f32_e32 v36, v165, v36
	v_exp_f32_e32 v169, v33
	v_sub_f32_e32 v33, v34, v142
	v_add_f32_e32 v36, v166, v36
	v_exp_f32_e32 v170, v33
	v_sub_f32_e32 v33, v35, v142
	v_add_f32_e32 v36, v167, v36
	v_exp_f32_e32 v171, v33
	v_add_f32_e32 v32, v168, v36
	v_add_f32_e32 v32, v169, v32
	v_add_f32_e32 v32, v170, v32
	v_add_f32_e32 v32, v171, v32
	ds_bpermute_b32 v33, v91, v32
	v_add_u32_e32 v50, 16, v154
	v_bitop3_b32 v36, s25, v93, v76 bitop3:0x36
	v_xor_b32_e32 v38, v50, v93
	v_bitop3_b32 v40, s25, v95, v76 bitop3:0x36
	s_waitcnt lgkmcnt(0)
	v_add_f32_e32 v32, v32, v33
	ds_bpermute_b32 v33, v92, v32
	v_xor_b32_e32 v42, v50, v95
	v_bitop3_b32 v44, s25, v96, v76 bitop3:0x36
	v_xor_b32_e32 v46, v50, v96
	v_bitop3_b32 v48, s25, v97, v76 bitop3:0x36
	s_waitcnt lgkmcnt(0)
; __device__ __forceinline__ u32x4 pack8(const f32x4 a, const f32x4 b) { u32x4 w; w.x = cvt_pk_bf16(a[0], a[1]); w.y = cvt_pk_bf16(a[2], a[3]); w.z = cvt_pk_bf16(b[0], b[1]); w.w = cvt_pk_bf16(b[2], b[3]); return w; }
; #define LAS __attribute__((address_space(3)))
; __device__ __forceinline__ void attn_phase(LAS unsigned char* lds, const bf16_t* QKVZ, const float* sinks, bf16_t* OG, int G, int bid, int tid) {
;     ...
;             sum += __shfl_xor(sum, 16); sum += __shfl_xor(sum, 32);
;             sum += __builtin_amdgcn_exp2f(sink2 - mx);
;             const float inv = 1.0f / sum;
;             f32x4 o[4];
; #pragma unroll
;             for (int dt = 0; dt < 4; ++dt) o[dt] = (f32x4){0.f, 0.f, 0.f, 0.f};
; #pragma unroll
;             for (int kk = 0; kk < 5; ++kk) {
;                 const u32x4 pw = pack8(s[2 * kk], s[2 * kk + 1]);
;                 const bf16x8 pf = __builtin_bit_cast(bf16x8, pw);
; #pragma unroll
;                 for (int dt = 0; dt < 4; ++dt) {
;                     const int d = dt * 16 + fr, sw = ((d >> 3) & 7) << 2, keyA = 16 * (kt0 + 2 * kk) + 4 * fq, keyB = keyA + 16;
;                     const u32x2 va = *(const LAS u32x2*)(Vt + d * VP + ((keyA ^ sw) * 2)), vb = *(const LAS u32x2*)(Vt + d * VP + ((keyB ^ sw) * 2));
;                     const u32x4 vw = (u32x4){va.x, va.y, vb.x, vb.y};
;                     o[dt] = __builtin_amdgcn_mfma_f32_16x16x32_bf16(__builtin_bit_cast(bf16x8, vw), pf, o[dt], 0, 0, 0);
;                 }
;             }
	v_add_f32_e32 v32, v32, v33
	v_sub_f32_e32 v33, v141, v142
	v_exp_f32_e32 v33, v33
	v_xor_b32_e32 v50, v50, v97
	v_lshl_add_u32 v36, v36, 1, v94
	v_lshl_add_u32 v38, v38, 1, v94
	v_lshl_add_u32 v40, v40, 1, v94
	v_lshl_add_u32 v42, v42, 1, v94
	v_lshl_add_u32 v44, v44, 1, v94
	v_lshl_add_u32 v46, v46, 1, v94
	v_lshl_add_u32 v48, v48, 1, v94
	v_lshl_add_u32 v50, v50, 1, v94
	v_add_f32_e32 v142, v33, v32
	v_cvt_pk_bf16_f32 v32, v68, v69
	v_cvt_pk_bf16_f32 v33, v70, v71
	v_cvt_pk_bf16_f32 v34, v64, v65
	v_cvt_pk_bf16_f32 v35, v66, v67
	ds_read_b64 v[36:37], v36 offset:36864
	ds_read_b64 v[38:39], v38 offset:36864
	ds_read_b64 v[40:41], v40 offset:45312
	ds_read_b64 v[42:43], v42 offset:45312
	ds_read_b64 v[44:45], v44 offset:53760
	ds_read_b64 v[46:47], v46 offset:53760
	ds_read_b64 v[48:49], v48 offset:62208
	ds_read_b64 v[50:51], v50 offset:62208
	s_waitcnt lgkmcnt(6)
	v_mfma_f32_16x16x32_bf16 v[36:39], v[36:39], v[32:35], 0
	v_bitop3_b32 v52, s29, v93, v76 bitop3:0x36
	v_lshl_add_u32 v52, v52, 1, v94
	s_waitcnt lgkmcnt(4)
	v_mfma_f32_16x16x32_bf16 v[40:43], v[40:43], v[32:35], 0
	s_waitcnt lgkmcnt(2)
	v_mfma_f32_16x16x32_bf16 v[44:47], v[44:47], v[32:35], 0
	s_waitcnt lgkmcnt(0)
	v_mfma_f32_16x16x32_bf16 v[32:35], v[48:51], v[32:35], 0
	v_cvt_pk_bf16_f32 v48, v60, v61
	v_cvt_pk_bf16_f32 v49, v62, v63
	v_cvt_pk_bf16_f32 v50, v56, v57
	v_add_u32_e32 v56, 16, v164
	v_xor_b32_e32 v54, v56, v93
	v_lshl_add_u32 v54, v54, 1, v94
	v_cvt_pk_bf16_f32 v51, v58, v59
	ds_read_b64 v[52:53], v52 offset:36864
	ds_read_b64 v[54:55], v54 offset:36864
	s_waitcnt lgkmcnt(0)
	v_mfma_f32_16x16x32_bf16 v[36:39], v[52:55], v[48:51], v[36:39]
	v_bitop3_b32 v52, s29, v95, v76 bitop3:0x36
	v_xor_b32_e32 v54, v56, v95
	v_lshl_add_u32 v52, v52, 1, v94
	v_lshl_add_u32 v54, v54, 1, v94
	ds_read_b64 v[52:53], v52 offset:45312
	ds_read_b64 v[54:55], v54 offset:45312
	s_waitcnt lgkmcnt(0)
	v_mfma_f32_16x16x32_bf16 v[40:43], v[52:55], v[48:51], v[40:43]
	v_bitop3_b32 v52, s29, v96, v76 bitop3:0x36
	v_xor_b32_e32 v54, v56, v96
	v_lshl_add_u32 v52, v52, 1, v94
	v_lshl_add_u32 v54, v54, 1, v94
	ds_read_b64 v[52:53], v52 offset:53760
	ds_read_b64 v[54:55], v54 offset:53760
	s_waitcnt lgkmcnt(0)
	v_mfma_f32_16x16x32_bf16 v[44:47], v[52:55], v[48:51], v[44:47]
	v_bitop3_b32 v52, s29, v97, v76 bitop3:0x36
	v_xor_b32_e32 v54, v56, v97
	v_lshl_add_u32 v52, v52, 1, v94
	v_lshl_add_u32 v54, v54, 1, v94
	ds_read_b64 v[52:53], v52 offset:62208
	ds_read_b64 v[54:55], v54 offset:62208
	v_add_u32_e32 v56, 16, v163
	s_waitcnt lgkmcnt(0)
	v_mfma_f32_16x16x32_bf16 v[32:35], v[52:55], v[48:51], v[32:35]
	v_bitop3_b32 v52, s28, v93, v76 bitop3:0x36
	v_xor_b32_e32 v54, v56, v93
	v_lshl_add_u32 v52, v52, 1, v94
	v_lshl_add_u32 v54, v54, 1, v94
	v_cvt_pk_bf16_f32 v48, v144, v143
	v_cvt_pk_bf16_f32 v49, v145, v146
	v_cvt_pk_bf16_f32 v50, v147, v148
	v_cvt_pk_bf16_f32 v51, v150, v151
	ds_read_b64 v[52:53], v52 offset:36864
	ds_read_b64 v[54:55], v54 offset:36864
	s_waitcnt lgkmcnt(0)
	v_mfma_f32_16x16x32_bf16 v[36:39], v[52:55], v[48:51], v[36:39]
	v_bitop3_b32 v52, s28, v95, v76 bitop3:0x36
	v_xor_b32_e32 v54, v56, v95
	v_lshl_add_u32 v52, v52, 1, v94
	v_lshl_add_u32 v54, v54, 1, v94
	ds_read_b64 v[52:53], v52 offset:45312
	ds_read_b64 v[54:55], v54 offset:45312
	s_waitcnt lgkmcnt(0)
	v_mfma_f32_16x16x32_bf16 v[40:43], v[52:55], v[48:51], v[40:43]
	v_bitop3_b32 v52, s28, v96, v76 bitop3:0x36
	v_xor_b32_e32 v54, v56, v96
	v_lshl_add_u32 v52, v52, 1, v94
	v_lshl_add_u32 v54, v54, 1, v94
	ds_read_b64 v[52:53], v52 offset:53760
	ds_read_b64 v[54:55], v54 offset:53760
	s_waitcnt lgkmcnt(0)
	v_mfma_f32_16x16x32_bf16 v[44:47], v[52:55], v[48:51], v[44:47]
	v_bitop3_b32 v52, s28, v97, v76 bitop3:0x36
	v_xor_b32_e32 v54, v56, v97
	v_lshl_add_u32 v52, v52, 1, v94
	v_lshl_add_u32 v54, v54, 1, v94
	ds_read_b64 v[52:53], v52 offset:62208
	ds_read_b64 v[54:55], v54 offset:62208
	v_add_u32_e32 v56, 16, v156
	s_waitcnt lgkmcnt(0)
	v_mfma_f32_16x16x32_bf16 v[32:35], v[52:55], v[48:51], v[32:35]
	v_bitop3_b32 v52, s27, v93, v76 bitop3:0x36
	v_xor_b32_e32 v54, v56, v93
	v_lshl_add_u32 v52, v52, 1, v94
	v_lshl_add_u32 v54, v54, 1, v94
	v_cvt_pk_bf16_f32 v48, v152, v153
	v_cvt_pk_bf16_f32 v49, v155, v157
	v_cvt_pk_bf16_f32 v50, v158, v159
	v_cvt_pk_bf16_f32 v51, v160, v161
	ds_read_b64 v[52:53], v52 offset:36864
	ds_read_b64 v[54:55], v54 offset:36864
	s_waitcnt lgkmcnt(0)
	v_mfma_f32_16x16x32_bf16 v[36:39], v[52:55], v[48:51], v[36:39]
	v_bitop3_b32 v52, s27, v95, v76 bitop3:0x36
	v_xor_b32_e32 v54, v56, v95
	v_lshl_add_u32 v52, v52, 1, v94
	v_lshl_add_u32 v54, v54, 1, v94
	ds_read_b64 v[52:53], v52 offset:45312
	ds_read_b64 v[54:55], v54 offset:45312
	s_waitcnt lgkmcnt(0)
	v_mfma_f32_16x16x32_bf16 v[40:43], v[52:55], v[48:51], v[40:43]
	v_bitop3_b32 v52, s27, v96, v76 bitop3:0x36
	v_xor_b32_e32 v54, v56, v96
	v_lshl_add_u32 v52, v52, 1, v94
	v_lshl_add_u32 v54, v54, 1, v94
	ds_read_b64 v[52:53], v52 offset:53760
	ds_read_b64 v[54:55], v54 offset:53760
	s_waitcnt lgkmcnt(0)
	v_mfma_f32_16x16x32_bf16 v[52:55], v[52:55], v[48:51], v[44:47]
	s_nop 2
	v_bitop3_b32 v44, s27, v97, v76 bitop3:0x36
	v_xor_b32_e32 v46, v56, v97
	v_lshl_add_u32 v44, v44, 1, v94
	v_lshl_add_u32 v46, v46, 1, v94
	ds_read_b64 v[44:45], v44 offset:62208
	ds_read_b64 v[46:47], v46 offset:62208
	v_add_u32_e32 v56, 16, v149
	s_waitcnt lgkmcnt(0)
	v_mfma_f32_16x16x32_bf16 v[32:35], v[44:47], v[48:51], v[32:35]
	v_bitop3_b32 v44, s26, v93, v76 bitop3:0x36
	v_xor_b32_e32 v46, v56, v93
	v_lshl_add_u32 v44, v44, 1, v94
	v_lshl_add_u32 v46, v46, 1, v94
	v_cvt_pk_bf16_f32 v48, v162, v165
	v_cvt_pk_bf16_f32 v49, v166, v167
	v_cvt_pk_bf16_f32 v50, v168, v169
	v_cvt_pk_bf16_f32 v51, v170, v171
	ds_read_b64 v[44:45], v44 offset:36864
	ds_read_b64 v[46:47], v46 offset:36864
	s_waitcnt lgkmcnt(0)
; __device__ __forceinline__ unsigned cvt_pk_bf16(float lo, float hi) { unsigned r; asm volatile("v_cvt_pk_bf16_f32 %0, %1, %2" : "=v"(r) : "v"(lo), "v"(hi)); return r; }
; __device__ __forceinline__ float bflo(unsigned w) { return __uint_as_float(w << 16); }
; __device__ __forceinline__ float bfhi(unsigned w) { return __uint_as_float(w & 0xffff0000u); }
; __device__ __forceinline__ float fsigmoid(float x) { return __builtin_amdgcn_rcpf(1.0f + __expf(-x)); }
; #define LAS __attribute__((address_space(3)))
; __device__ __forceinline__ void attn_phase(LAS unsigned char* lds, const bf16_t* QKVZ, const float* sinks, bf16_t* OG, int G, int bid, int tid) {
;     ...
;             const float inv = 1.0f / sum;
;             f32x4 o[4];
; #pragma unroll
;             for (int dt = 0; dt < 4; ++dt) o[dt] = (f32x4){0.f, 0.f, 0.f, 0.f};
; #pragma unroll
;             for (int kk = 0; kk < 5; ++kk) {
;                 const u32x4 pw = pack8(s[2 * kk], s[2 * kk + 1]);
;                 const bf16x8 pf = __builtin_bit_cast(bf16x8, pw);
; #pragma unroll
;                 for (int dt = 0; dt < 4; ++dt) {
;                     const int d = dt * 16 + fr, sw = ((d >> 3) & 7) << 2, keyA = 16 * (kt0 + 2 * kk) + 4 * fq, keyB = keyA + 16;
;                     const u32x2 va = *(const LAS u32x2*)(Vt + d * VP + ((keyA ^ sw) * 2)), vb = *(const LAS u32x2*)(Vt + d * VP + ((keyB ^ sw) * 2));
;                     const u32x4 vw = (u32x4){va.x, va.y, vb.x, vb.y};
;                     o[dt] = __builtin_amdgcn_mfma_f32_16x16x32_bf16(__builtin_bit_cast(bf16x8, vw), pf, o[dt], 0, 0, 0);
;                 }
;             }
;             const bf16_t* zp = QKVZ + row * ATT_IN + 1536 + h * 64 + 4 * fq;
;             bf16_t* op = OG + row * D + h * 64 + 4 * fq;
; #pragma unroll
;             for (int dt = 0; dt < 4; ++dt) {
;                 const u32x2 zw = *(const u32x2*)(zp + dt * 16);
;                 const float z0 = bflo(zw.x), z1 = bfhi(zw.x), z2 = bflo(zw.y), z3 = bfhi(zw.y);
;                 const float r0 = o[dt][0] * inv * z0 * fsigmoid(z0), r1 = o[dt][1] * inv * z1 * fsigmoid(z1), r2 = o[dt][2] * inv * z2 * fsigmoid(z2), r3 = o[dt][3] * inv * z3 * fsigmoid(z3);
;                 u32x2 w; w.x = cvt_pk_bf16(r0, r1); w.y = cvt_pk_bf16(r2, r3);
;                 *(u32x2*)(op + dt * 16) = w;
;             }
	v_mfma_f32_16x16x32_bf16 v[44:47], v[44:47], v[48:51], v[36:39]
	s_nop 2
	v_bitop3_b32 v36, s26, v95, v76 bitop3:0x36
	v_xor_b32_e32 v38, v56, v95
	v_lshl_add_u32 v36, v36, 1, v94
	v_lshl_add_u32 v38, v38, 1, v94
	ds_read_b64 v[36:37], v36 offset:45312
	ds_read_b64 v[38:39], v38 offset:45312
	s_waitcnt lgkmcnt(0)
	v_mfma_f32_16x16x32_bf16 v[40:43], v[36:39], v[48:51], v[40:43]
	v_bitop3_b32 v36, s26, v96, v76 bitop3:0x36
	v_xor_b32_e32 v38, v56, v96
	v_lshl_add_u32 v36, v36, 1, v94
	v_lshl_add_u32 v38, v38, 1, v94
	ds_read_b64 v[36:37], v36 offset:53760
	ds_read_b64 v[38:39], v38 offset:53760
	s_waitcnt lgkmcnt(0)
	v_mfma_f32_16x16x32_bf16 v[36:39], v[36:39], v[48:51], v[52:55]
	s_nop 2
	v_bitop3_b32 v52, s26, v97, v76 bitop3:0x36
	v_xor_b32_e32 v54, v56, v97
	v_lshl_add_u32 v52, v52, 1, v94
	v_lshl_add_u32 v54, v54, 1, v94
	ds_read_b64 v[52:53], v52 offset:62208
	ds_read_b64 v[54:55], v54 offset:62208
	s_waitcnt lgkmcnt(0)
	v_mfma_f32_16x16x32_bf16 v[32:35], v[52:55], v[48:51], v[32:35]
	v_div_scale_f32 v48, s[26:27], v142, v142, 1.0
	v_rcp_f32_e32 v49, v48
	s_nop 0
	v_fma_f32 v50, -v48, v49, 1.0
	v_fmac_f32_e32 v49, v50, v49
	v_div_scale_f32 v50, vcc, 1.0, v142, 1.0
	v_mul_f32_e32 v51, v50, v49
	v_fma_f32 v52, -v48, v51, v50
	v_fmac_f32_e32 v51, v52, v49
	v_fma_f32 v48, -v48, v51, v50
	v_div_fmas_f32 v48, v48, v49, v51
	v_div_fixup_f32 v52, v48, v142, 1.0
	v_lshlrev_b32_e32 v48, 1, v76
	v_mov_b32_e32 v49, v73
	v_lshl_add_u64 v[50:51], v[84:85], 0, v[48:49]
	v_mul_f32_e32 v44, v52, v44
	v_mul_f32_e32 v45, v52, v45
	v_mul_f32_e32 v46, v52, v46
	v_mul_f32_e32 v47, v52, v47
	v_lshlrev_b64 v[48:49], 11, v[82:83]
	v_lshl_add_u64 v[48:49], v[80:81], 0, v[48:49]
	v_mul_f32_e32 v41, v52, v41
	v_mul_f32_e32 v40, v52, v40
	v_mul_f32_e32 v42, v52, v42
	v_mul_f32_e32 v43, v52, v43
	v_mul_f32_e32 v37, v52, v37
	v_mul_f32_e32 v36, v52, v36
	v_mul_f32_e32 v38, v52, v38
	v_mul_f32_e32 v39, v52, v39
	v_mul_f32_e32 v33, v52, v33
	v_mul_f32_e32 v32, v52, v32
	v_mul_f32_e32 v34, v52, v34
	v_mul_f32_e32 v35, v52, v35
	s_waitcnt vmcnt(0)
	v_mov_b64_e32 v[54:55], v[200:201]
	v_lshlrev_b32_e32 v53, 16, v54
	v_mul_f32_e32 v44, v44, v53
	v_mul_f32_e32 v53, 0xbfb8aa3b, v53
	v_exp_f32_e32 v53, v53
	v_and_b32_e32 v54, 0xffff0000, v54
	v_lshlrev_b32_e32 v56, 16, v55
	v_mul_f32_e32 v45, v45, v54
	v_add_f32_e32 v53, 1.0, v53
	v_rcp_f32_e32 v53, v53
	v_and_b32_e32 v55, 0xffff0000, v55
	v_mul_f32_e32 v46, v46, v56
	v_mul_f32_e32 v47, v47, v55
	v_mul_f32_e32 v44, v44, v53
	v_mul_f32_e32 v53, 0xbfb8aa3b, v54
	v_exp_f32_e32 v53, v53
	s_nop 0
	v_add_f32_e32 v53, 1.0, v53
	v_rcp_f32_e32 v53, v53
	s_nop 0
	v_mul_f32_e32 v45, v45, v53
	v_mul_f32_e32 v53, 0xbfb8aa3b, v56
	v_exp_f32_e32 v53, v53
	v_cvt_pk_bf16_f32 v44, v44, v45
	s_nop 0
	v_add_f32_e32 v53, 1.0, v53
	v_rcp_f32_e32 v53, v53
	s_nop 0
	v_mul_f32_e32 v46, v46, v53
	v_mul_f32_e32 v53, 0xbfb8aa3b, v55
	v_exp_f32_e32 v53, v53
	s_nop 0
	v_add_f32_e32 v53, 1.0, v53
	v_rcp_f32_e32 v53, v53
	s_nop 0
	v_mul_f32_e32 v47, v47, v53
	v_cvt_pk_bf16_f32 v45, v46, v47
	global_store_dwordx2 v[48:49], v[44:45], off
	s_nop 1
	v_mov_b64_e32 v[44:45], v[202:203]
	v_lshlrev_b32_e32 v46, 16, v44
	v_and_b32_e32 v44, 0xffff0000, v44
	v_mul_f32_e32 v41, v41, v44
	v_mul_f32_e32 v44, 0xbfb8aa3b, v44
	v_exp_f32_e32 v44, v44
	v_lshlrev_b32_e32 v47, 16, v45
	v_and_b32_e32 v45, 0xffff0000, v45
	v_mul_f32_e32 v40, v40, v46
	v_add_f32_e32 v44, 1.0, v44
	v_rcp_f32_e32 v44, v44
	v_mul_f32_e32 v46, 0xbfb8aa3b, v46
	v_mul_f32_e32 v42, v42, v47
	v_exp_f32_e32 v46, v46
	v_mul_f32_e32 v41, v41, v44
	v_mul_f32_e32 v44, 0xbfb8aa3b, v47
	v_exp_f32_e32 v44, v44
	v_add_f32_e32 v46, 1.0, v46
	v_rcp_f32_e32 v46, v46
	v_mul_f32_e32 v43, v43, v45
	v_add_f32_e32 v44, 1.0, v44
	v_rcp_f32_e32 v44, v44
	v_mul_f32_e32 v40, v40, v46
	v_cvt_pk_bf16_f32 v40, v40, v41
	v_mul_f32_e32 v42, v42, v44
	v_mul_f32_e32 v44, 0xbfb8aa3b, v45
	v_exp_f32_e32 v44, v44
	s_nop 0
	v_add_f32_e32 v44, 1.0, v44
	v_rcp_f32_e32 v44, v44
	s_nop 0
	v_mul_f32_e32 v43, v43, v44
	v_cvt_pk_bf16_f32 v41, v42, v43
	global_store_dwordx2 v[48:49], v[40:41], off offset:32
	s_nop 1
	v_mov_b64_e32 v[40:41], v[204:205]
	v_lshlrev_b32_e32 v42, 16, v40
	v_and_b32_e32 v40, 0xffff0000, v40
	v_mul_f32_e32 v37, v37, v40
	v_mul_f32_e32 v40, 0xbfb8aa3b, v40
	v_exp_f32_e32 v40, v40
	v_lshlrev_b32_e32 v43, 16, v41
	v_and_b32_e32 v41, 0xffff0000, v41
	v_mul_f32_e32 v36, v36, v42
	v_add_f32_e32 v40, 1.0, v40
	v_rcp_f32_e32 v40, v40
	v_mul_f32_e32 v42, 0xbfb8aa3b, v42
	v_mul_f32_e32 v38, v38, v43
	v_exp_f32_e32 v42, v42
	v_mul_f32_e32 v37, v37, v40
	v_mul_f32_e32 v40, 0xbfb8aa3b, v43
	v_exp_f32_e32 v40, v40
	v_add_f32_e32 v42, 1.0, v42
	v_rcp_f32_e32 v42, v42
	v_mul_f32_e32 v39, v39, v41
	v_add_f32_e32 v40, 1.0, v40
	v_rcp_f32_e32 v40, v40
	v_mul_f32_e32 v36, v36, v42
	v_cvt_pk_bf16_f32 v36, v36, v37
	v_mul_f32_e32 v38, v38, v40
	v_mul_f32_e32 v40, 0xbfb8aa3b, v41
	v_exp_f32_e32 v40, v40
	s_nop 0
	v_add_f32_e32 v40, 1.0, v40
	v_rcp_f32_e32 v40, v40
	s_nop 0
	v_mul_f32_e32 v39, v39, v40
	v_cvt_pk_bf16_f32 v37, v38, v39
	global_store_dwordx2 v[48:49], v[36:37], off offset:64
	s_nop 1
	v_mov_b64_e32 v[36:37], v[206:207]
	v_lshlrev_b32_e32 v38, 16, v36
	v_and_b32_e32 v36, 0xffff0000, v36
	v_mul_f32_e32 v33, v33, v36
	v_mul_f32_e32 v36, 0xbfb8aa3b, v36
	v_exp_f32_e32 v36, v36
	v_lshlrev_b32_e32 v39, 16, v37
	v_and_b32_e32 v37, 0xffff0000, v37
	v_mul_f32_e32 v32, v32, v38
	v_add_f32_e32 v36, 1.0, v36
	v_rcp_f32_e32 v36, v36
	v_mul_f32_e32 v38, 0xbfb8aa3b, v38
	v_mul_f32_e32 v34, v34, v39
	v_exp_f32_e32 v38, v38
	v_mul_f32_e32 v33, v33, v36
	v_mul_f32_e32 v36, 0xbfb8aa3b, v39
	v_exp_f32_e32 v36, v36
	v_add_f32_e32 v38, 1.0, v38
	v_rcp_f32_e32 v38, v38
	v_mul_f32_e32 v35, v35, v37
	v_add_f32_e32 v36, 1.0, v36
	v_rcp_f32_e32 v36, v36
	v_mul_f32_e32 v32, v32, v38
	v_cvt_pk_bf16_f32 v32, v32, v33
	v_mul_f32_e32 v34, v34, v36
	v_mul_f32_e32 v36, 0xbfb8aa3b, v37
	v_exp_f32_e32 v36, v36
	s_nop 0
	v_add_f32_e32 v36, 1.0, v36
	v_rcp_f32_e32 v36, v36
	s_nop 0
	v_mul_f32_e32 v35, v35, v36
	v_cvt_pk_bf16_f32 v33, v34, v35
	global_store_dwordx2 v[48:49], v[32:33], off offset:96
	s_cbranch_scc0 .LBB0_246
	s_add_i32 s16, s16, s21
	s_and_b64 vcc, exec, s[10:11]
	s_mov_b32 s12, s24
	s_cbranch_vccz .LBB0_235

; #define LAS __attribute__((address_space(3)))
; __device__ __forceinline__ void scan_phase(LAS unsigned char* lds, const bf16_t* R, const bf16_t* Kb, const bf16_t* V, const bf16_t* WA, const float* k_k, const float* k_a, bf16_t* Y, int G, int bid, int tid) {
;     const int wave = __builtin_amdgcn_readfirstlane(tid >> 6), lane = tid & 63, c = lane & 15, g = lane >> 4;
;     const int wq = (wave & 1) + ((wave >> 2) << 1);
;     const int pid = wq * 64 + lane, pt = (pid >> 4) & 15, pj = pid & 15;
;     const int pid1 = tid - 256, pta = (pid1 >> 4) & 7, ptb = pta + 8;
;     const bool producer = (wave == 2) || (wave == 3) || (wave >= 6), producer1 = (wave == 4) || (wave == 5), consumer = wave < 2;
;     constexpr int NCH = T / 16;
;     for (int unit = bid; unit < 256; unit += G) {
;         const int b = unit >> 5, h = (unit >> 1) & 15, half = unit & 1;
;         const size_t rowbase = (size_t)b * T;
;         f32x4 kkw = (f32x4){0.f, 0.f, 0.f, 0.f}, kaw = kkw;
;         if (producer1) { kkw = *(const f32x4*)(k_k + h * 64 + 4 * pj); kaw = *(const f32x4*)(k_a + h * 64 + 4 * pj); }
;         u32x2 rkA = (u32x2){0u, 0u}, rrA = rkA, raA = rkA, rlA = rkA, rkB = rkA, rrB = rkA, raB = rkA, rlB = rkA; unsigned rvA = 0u, rvB = 0u;
.LBB0_873:
	v_readlane_b32 s2, v254, 1
	v_readlane_b32 s3, v254, 2
	s_cmp_lt_i32 s2, 11
	s_cselect_b64 s[2:3], -1, 0
	s_and_b64 s[4:5], s[2:3], s[0:1]
	s_andn2_b64 vcc, exec, s[4:5]
	s_cbranch_vccnz .LBB0_952
	v_mbcnt_lo_u32_b32 v1, -1, 0
	v_mbcnt_hi_u32_b32 v1, -1, v1
	s_lshr_b32 s98, s52, 4
	s_lshr_b32 s98, 0x63725410, s98
	s_and_b32 s98, s98, 7
	s_lshl_b32 s98, s98, 6
	s_cmpk_gt_i32 s84, 0xff
	v_add_u32_e32 v2, s98, v1
	s_mov_b64 s[0:1], s[82:83]
	v_readfirstlane_b32 s2, v2
	s_cbranch_scc1 .LBB0_952
	v_writelane_b32 v254, s4, 4
	v_and_b32_e32 v4, 63, v1
	v_and_b32_e32 v6, 15, v1
	v_writelane_b32 v254, s5, 5
	s_load_dwordx4 s[56:59], s[0:1], 0xc0
	s_load_dwordx4 s[4:7], s[0:1], 0x78
	s_load_dwordx2 s[100:101], s[0:1], 0x88
	v_writelane_b32 v254, s82, 6
	v_bfe_u32 v98, v2, 4, 3
	v_lshlrev_b32_e32 v2, 2, v2
	s_waitcnt lgkmcnt(0)
	s_add_u32 s64, s58, 0x16000000
	s_addc_u32 s65, s59, 0
	s_add_u32 s66, s56, 0x4000000
	s_addc_u32 s67, s57, 0
	s_add_u32 s68, s58, 0x8000000
	s_addc_u32 s69, s59, 0
	s_ashr_i32 s10, s2, 6
	s_and_b32 s3, s2, 0xffffff80
	s_cmpk_eq_i32 s3, 0x80
	s_cselect_b64 s[0:1], -1, 0
	s_cmp_gt_i32 s10, 5
	s_cselect_b64 s[8:9], -1, 0
	s_or_b64 s[70:71], s[0:1], s[8:9]
	s_cmpk_eq_i32 s3, 0x100
	s_cselect_b64 s[72:73], -1, 0
	s_cmpk_lg_i32 s3, 0x100
	v_writelane_b32 v254, s83, 7
	s_cselect_b64 s[0:1], -1, 0
	s_cmp_lt_i32 s10, 2
	v_writelane_b32 v254, s0, 8
	s_cselect_b64 s[76:77], -1, 0
	s_ashr_i32 s8, s2, 7
	v_writelane_b32 v254, s1, 9
	s_and_b32 s0, s10, 1
	s_and_b32 s1, s8, -2
	s_or_b32 s30, s0, s1
	s_mul_i32 s0, s10, 0xa00
	v_lshl_or_b32 v0, s30, 6, v4
	s_add_i32 s33, s0, 0
	s_lshl_b32 s0, s10, 4
	v_bfe_u32 v5, v0, 4, 4
	v_mov_b32_e32 v0, 0
	s_lshl_b32 s31, s30, 2
	s_ashr_i32 s1, s0, 31
	v_and_b32_e32 v103, 0x1fc, v2
	v_lshlrev_b32_e32 v2, 3, v6
	v_mov_b32_e32 v3, v0
	s_cmp_gt_i32 s8, -1
	v_lshl_add_u64 v[112:113], s[56:57], 0, v[2:3]
	v_lshl_add_u64 v[114:115], s[64:65], 0, v[2:3]
	v_lshlrev_b32_e32 v3, 4, v1
	s_cselect_b64 s[8:9], -1, 0
	s_cmp_lg_u32 s30, 0
	v_bfe_u32 v7, v1, 4, 2
	v_lshlrev_b32_e32 v102, 2, v6
	v_and_b32_e32 v165, 48, v3
	v_lshlrev_b32_e32 v3, 1, v1
	s_cselect_b64 s[82:83], -1, 0
	s_cmp_gt_i32 s30, 0
	v_and_b32_e32 v166, 8, v3
	v_or_b32_e32 v3, v102, v7
	s_mov_b32 s75, s84
	s_cselect_b64 s[84:85], -1, 0
	s_cmp_lt_u32 s31, 5
	v_mul_u32_u24_e32 v3, 40, v3
	s_cselect_b64 s[86:87], -1, 0
	s_cmp_gt_i32 s30, 1
	v_lshlrev_b32_e32 v104, 4, v6
	v_mov_b32_e32 v105, v0
	v_lshl_add_u32 v167, s30, 3, v3
	v_and_b32_e32 v171, 48, v1
	v_lshlrev_b32_e32 v3, 2, v7
	v_and_b32_e32 v1, 16, v1
	s_cselect_b64 s[88:89], -1, 0
	s_cmp_lt_u32 s31, 9
	v_lshl_add_u64 v[108:109], s[4:5], 0, v[104:105]
	v_lshl_add_u64 v[206:207], s[100:101], 0, v[104:105]
	v_cmp_eq_u32_e64 s[4:5], 0, v1
	s_cselect_b64 s[90:91], -1, 0
	s_cmp_gt_i32 s30, 2
	v_or_b32_e32 v1, 1, v3
	v_or_b32_e32 v100, 8, v98
	s_cselect_b64 s[92:93], -1, 0
	s_cmp_lt_u32 s31, 13
	v_cmp_lt_u32_e32 vcc, v1, v6
	v_or_b32_e32 v1, 2, v3
	v_lshlrev_b32_e32 v155, 6, v100
	v_lshlrev_b32_e32 v161, 8, v5
	s_cselect_b64 s[94:95], -1, 0
	v_cmp_lt_u32_e64 s[48:49], v1, v6
	v_cmp_gt_u32_e64 s[42:43], v1, v6
	v_or_b32_e32 v1, 3, v3
	s_add_i32 s51, 0, 0x13400
	v_cmp_lt_u32_e64 s[44:45], v1, v6
	v_cmp_gt_u32_e64 s[46:47], v1, v6
	v_add_u32_e32 v1, s51, v155
	v_add_u32_e32 v178, 0, v161
	s_movk_i32 s51, 0xff40
	s_movk_i32 s50, 0x50
	v_writelane_b32 v254, s8, 10
	v_mad_i32_i24 v179, v5, s51, v178
	v_lshl_add_u64 v[106:107], s[6:7], 0, v[104:105]
	v_lshlrev_b32_e32 v162, 6, v5
	v_mul_u32_u24_e32 v163, 0x90, v5
	v_lshlrev_b32_e32 v169, 1, v5
	v_cmp_eq_u32_e64 s[2:3], 15, v5
	v_cmp_gt_u32_e64 s[6:7], 32, v4
	v_writelane_b32 v254, s9, 11
	v_cmp_eq_u32_e64 s[8:9], 0, v5
	v_cmp_gt_u32_e64 s[10:11], 2, v5
	v_cmp_gt_u32_e64 s[12:13], 3, v5
	v_cmp_gt_u32_e64 s[14:15], 4, v5
	v_cmp_lt_u32_e64 s[16:17], 4, v5
	v_cmp_gt_u32_e64 s[18:19], 6, v5
	v_cmp_gt_u32_e64 s[20:21], 7, v5
	v_cmp_gt_u32_e64 s[22:23], 8, v5
	v_cmp_lt_u32_e64 s[24:25], 8, v5
	v_cmp_gt_u32_e64 s[26:27], 10, v5
	v_cmp_gt_u32_e64 s[28:29], 11, v5
	v_cmp_gt_u32_e64 s[30:31], 12, v5
	v_cmp_lt_u32_e64 s[34:35], 12, v5
	v_cmp_gt_u32_e64 s[36:37], 14, v5
	v_cmp_lt_u32_e64 s[38:39], v3, v6
	v_cmp_gt_u32_e64 s[40:41], v3, v6
	v_mad_u32_u24 v3, v5, s50, v179
	v_lshlrev_b32_e32 v4, 13, v7
	v_mov_b32_e32 v5, v0
	v_lshlrev_b32_e32 v110, 1, v6
	v_lshl_add_u64 v[4:5], s[0:1], 1, v[4:5]
	v_or_b32_e32 v4, v4, v110
	v_lshlrev_b32_e32 v9, 8, v7
	v_lshl_add_u64 v[116:117], s[58:59], 0, v[4:5]
	v_lshl_or_b32 v4, v98, 12, v2
	v_mov_b32_e32 v5, v0
	v_and_b32_e32 v164, 64, v2
	v_add3_u32 v172, s33, v9, v102
	v_or_b32_e32 v9, s0, v6
	v_lshl_add_u64 v[4:5], s[58:59], 0, v[4:5]
	s_mov_b64 s[0:1], 0x8038800
	v_mul_lo_u32 v173, v9, 40
	v_add3_u32 v9, v3, v164, v165
	v_lshlrev_b32_e32 v3, 6, v6
	v_lshl_add_u64 v[118:119], v[4:5], 0, s[0:1]
	v_lshlrev_b32_e32 v4, 11, v98
	v_lshl_or_b32 v99, v98, 8, v104
	v_lshl_or_b32 v105, v100, 8, v104
	v_mul_u32_u24_e32 v168, 0x50, v6
	v_mul_u32_u24_e32 v170, 0x90, v6
	v_mul_u32_u24_e32 v175, 40, v6
	v_mad_u32_u24 v180, v6, s50, 0
	v_sub_u32_e32 v6, 0, v3
	v_or_b32_e32 v2, v4, v2
	v_mov_b32_e32 v3, v0
	v_add_u32_e32 v101, 0, v99
	v_add_u32_e32 v111, 0, v105
	v_add_u32_e32 v8, 0, v155
	v_lshl_add_u64 v[120:121], s[56:57], 0, v[2:3]
	v_lshl_add_u64 v[122:123], s[58:59], 0, v[2:3]
	v_or_b32_e32 v2, v4, v102
	s_or_b64 s[48:49], s[44:45], s[48:49]
	s_mov_b32 s79, 0
	v_add_u32_e32 v160, 0, v104
	v_lshlrev_b32_e32 v174, 3, v7
	v_add_u32_e32 v176, 0xf400, v101
	v_add_u32_e32 v177, 0xf400, v111
	v_lshl_add_u64 v[124:125], s[56:57], 0, v[2:3]
	s_mov_b32 s74, 0x179abe15
	v_add_u32_e32 v181, v9, v166
	v_add_u32_e32 v181, 0x14000, v181
	v_add_u32_e32 v182, v180, v6
	v_add_u32_e32 v182, 0x14000, v182
	s_xor_b64 s[58:59], s[70:71], -1
	v_mov_b32_e32 v183, 0x5368d4a5
	v_add_u32_e32 v184, v8, v102
	v_add_u32_e32 v185, v1, v102
	s_or_b64 s[50:51], s[48:49], vcc
	v_writelane_b32 v254, s75, 12
	s_branch .LBB0_877

; __device__ __forceinline__ void scan_phase(LAS unsigned char* lds, const bf16_t* R, const bf16_t* Kb, const bf16_t* V, const bf16_t* WA, const float* k_k, const float* k_a, bf16_t* Y, int G, int bid, int tid) {
;     ...
;     for (int unit = bid; unit < 256; unit += G) {
;         const int b = unit >> 5, h = (unit >> 1) & 15, half = unit & 1;
;         const size_t rowbase = (size_t)b * T;
;         f32x4 kkw = (f32x4){0.f, 0.f, 0.f, 0.f}, kaw = kkw;
;         if (producer1) { kkw = *(const f32x4*)(k_k + h * 64 + 4 * pj); kaw = *(const f32x4*)(k_a + h * 64 + 4 * pj); }
.LBB0_877:
	v_cndmask_b32_e64 v1, 0, 1, s[72:73]
	s_bfe_u32 s80, s75, 0x40001
	v_cmp_ne_u32_e64 s[52:53], 1, v1
	s_andn2_b64 vcc, exec, s[72:73]
	v_mov_b32_e32 v4, v0
	v_mov_b32_e32 v5, v0
	v_mov_b32_e32 v6, v0
	v_mov_b32_e32 v7, v0
	v_mov_b32_e32 v8, v0
	v_mov_b32_e32 v9, v0
	v_mov_b32_e32 v10, v0
	v_mov_b32_e32 v11, v0
	s_cbranch_vccnz .LBB0_879
	s_lshl_b32 s78, s80, 8
	v_lshl_add_u64 v[2:3], v[108:109], 0, s[78:79]
	v_lshl_add_u64 v[4:5], v[106:107], 0, s[78:79]
	global_load_dwordx4 v[8:11], v[2:3], off
	s_nop 0
	global_load_dwordx4 v[4:7], v[4:5], off
	v_lshl_add_u64 v[212:213], v[206:207], 0, s[78:79]
	global_load_dwordx4 v[208:211], v[212:213], off
	s_lshr_b32 s98, s75, 5
	s_lshl_b32 s98, s98, 18
	s_lshl_b32 s99, s80, 2
	s_add_i32 s98, s98, s99
	s_sub_u32 s100, s64, 0x5800000
	s_subb_u32 s101, s65, 0
	v_lshl_add_u32 v214, v98, 6, s98
	v_mov_b32_e32 v215, 0
	v_lshl_add_u64 v[214:215], s[100:101], 0, v[214:215]

; __device__ __forceinline__ void scan_phase(LAS unsigned char* lds, const bf16_t* R, const bf16_t* Kb, const bf16_t* V, const bf16_t* WA, const float* k_k, const float* k_a, bf16_t* Y, int G, int bid, int tid) {
;     ...
;         if (producer1) { CK_LOAD(A, pta, 0); CK_LOAD(B, ptb, 0); CK_P1(A, pta, 0); CK_P1(B, ptb, 0); CK_LOAD(A, pta, 1); CK_LOAD(B, ptb, 1); }
.LBB0_881:
	s_ashr_i32 s96, s75, 5
	s_ashr_i32 s97, s96, 31
	s_lshl_b64 s[0:1], s[96:97], 12
	s_andn2_b64 vcc, exec, s[62:63]
	v_add_u32_e32 v22, 0, v103
	v_lshlrev_b32_e32 v2, 1, v102
	v_lshlrev_b32_e32 v12, 1, v110
	s_cbranch_vccnz .LBB0_883
	v_mov_b32_e32 v17, s1
	v_or_b32_e32 v16, s0, v98
	v_lshlrev_b64 v[24:25], 11, v[16:17]
	v_lshl_add_u64 v[14:15], s[56:57], 0, v[24:25]
	s_lshl_b32 s62, s80, 7
	s_mov_b32 s63, s79
	v_lshl_add_u64 v[14:15], v[14:15], 0, s[62:63]
	v_mov_b32_e32 v3, v0
	v_lshlrev_b64 v[16:17], 12, v[16:17]
	v_lshl_add_u64 v[14:15], v[14:15], 0, v[2:3]
	v_lshl_add_u64 v[16:17], s[68:69], 0, v[16:17]
	global_load_dwordx2 v[14:15], v[14:15], off
	v_lshl_add_u64 v[16:17], v[16:17], 0, s[62:63]
	v_lshl_add_u64 v[16:17], v[16:17], 0, v[2:3]
	v_mov_b32_e32 v27, s1
	v_or_b32_e32 v26, s0, v100
	global_load_dwordx2 v[20:21], v[16:17], off offset:2048
	global_load_dwordx2 v[18:19], v[16:17], off
	v_lshl_add_u64 v[16:17], s[64:65], 0, v[24:25]
	v_lshlrev_b64 v[30:31], 11, v[26:27]
	v_lshl_add_u64 v[24:25], s[66:67], 0, v[24:25]
	s_lshl_b32 vcc_lo, s81, 6
	s_mov_b32 vcc_hi, s79
	v_lshl_add_u64 v[32:33], s[56:57], 0, v[30:31]
	v_lshl_add_u64 v[24:25], v[24:25], 0, s[62:63]
	v_lshl_add_u64 v[16:17], v[16:17], 0, s[62:63]
	v_mov_b32_e32 v13, v0
	v_lshlrev_b64 v[26:27], 12, v[26:27]
	v_lshl_add_u64 v[34:35], s[64:65], 0, v[30:31]
	v_lshl_add_u64 v[32:33], v[32:33], 0, s[62:63]
	v_lshl_add_u64 v[24:25], v[24:25], 0, vcc
	v_lshl_add_u64 v[16:17], v[16:17], 0, v[2:3]
	v_lshl_add_u64 v[26:27], s[68:69], 0, v[26:27]
	v_lshl_add_u64 v[34:35], v[34:35], 0, s[62:63]
	v_lshl_add_u64 v[32:33], v[32:33], 0, v[2:3]
	v_lshl_add_u64 v[24:25], v[24:25], 0, v[12:13]
	global_load_dwordx2 v[16:17], v[16:17], off
	v_lshl_add_u64 v[26:27], v[26:27], 0, s[62:63]
	global_load_dword v1, v[24:25], off
	v_lshl_add_u64 v[24:25], v[34:35], 0, v[2:3]
	global_load_dwordx2 v[32:33], v[32:33], off
	v_lshl_add_u64 v[26:27], v[26:27], 0, v[2:3]
	global_load_dwordx2 v[34:35], v[24:25], off
	global_load_dwordx2 v[40:41], v[26:27], off
	global_load_dwordx2 v[42:43], v[26:27], off offset:2048
	s_lshl_b32 s78, s80, 6
	s_or_b32 s80, s0, 16
	v_mov_b32_e32 v29, s1
	v_or_b32_e32 v28, s80, v98
	v_lshlrev_b64 v[36:37], 11, v[28:29]
	v_lshl_add_u64 v[30:31], s[66:67], 0, v[30:31]
	v_lshl_add_u64 v[38:39], s[56:57], 0, v[36:37]
	v_lshl_add_u64 v[24:25], s[64:65], 0, v[36:37]
	v_lshl_add_u64 v[36:37], s[66:67], 0, v[36:37]
	v_lshlrev_b64 v[28:29], 12, v[28:29]
	v_lshl_add_u64 v[30:31], v[30:31], 0, s[62:63]
	v_lshl_add_u64 v[36:37], v[36:37], 0, s[62:63]
	v_lshl_add_u64 v[26:27], s[68:69], 0, v[28:29]
	v_lshl_add_u64 v[28:29], v[30:31], 0, vcc
	v_lshl_add_u64 v[24:25], v[24:25], 0, s[62:63]
	v_lshl_add_u64 v[36:37], v[36:37], 0, vcc
	v_lshl_add_u64 v[30:31], v[38:39], 0, s[62:63]
	v_lshl_add_u64 v[26:27], v[26:27], 0, s[62:63]
	v_lshl_add_u64 v[28:29], v[28:29], 0, v[12:13]
	v_lshl_add_u64 v[38:39], v[24:25], 0, v[2:3]
	v_lshl_add_u64 v[36:37], v[36:37], 0, v[12:13]
	v_lshl_add_u64 v[30:31], v[30:31], 0, v[2:3]
	v_lshl_add_u64 v[44:45], v[26:27], 0, v[2:3]
	global_load_dword v23, v[28:29], off
	global_load_dwordx2 v[134:135], v[30:31], off
	global_load_dwordx2 v[136:137], v[38:39], off
	global_load_dwordx2 v[138:139], v[44:45], off
	global_load_dwordx2 v[140:141], v[44:45], off offset:2048
	global_load_dword v187, v[36:37], off
	v_mov_b32_e32 v37, s1
	v_or_b32_e32 v36, s80, v100
	v_lshlrev_b64 v[38:39], 11, v[36:37]
	v_lshl_add_u64 v[44:45], s[56:57], 0, v[38:39]
	v_lshl_add_u64 v[44:45], v[44:45], 0, s[62:63]
	v_lshl_add_u64 v[44:45], v[44:45], 0, v[2:3]
	v_lshlrev_b64 v[36:37], 12, v[36:37]
	global_load_dwordx2 v[126:127], v[44:45], off
	v_lshl_add_u64 v[44:45], s[64:65], 0, v[38:39]
	v_lshl_add_u64 v[36:37], s[68:69], 0, v[36:37]
	v_lshl_add_u64 v[44:45], v[44:45], 0, s[62:63]
	v_lshl_add_u64 v[36:37], v[36:37], 0, s[62:63]
	v_lshl_add_u64 v[44:45], v[44:45], 0, v[2:3]
	v_lshl_add_u64 v[36:37], v[36:37], 0, v[2:3]
	global_load_dwordx2 v[128:129], v[44:45], off
	global_load_dwordx2 v[130:131], v[36:37], off
	global_load_dwordx2 v[132:133], v[36:37], off offset:2048
	v_lshl_add_u64 v[36:37], s[66:67], 0, v[38:39]
	v_lshl_add_u64 v[36:37], v[36:37], 0, s[62:63]
	v_lshl_add_u64 v[36:37], v[36:37], 0, vcc
	v_lshl_add_u64 v[36:37], v[36:37], 0, v[12:13]
	global_load_dword v186, v[36:37], off
	s_lshl_b32 s60, s81, 5
	s_mov_b32 s61, s79
	s_waitcnt vmcnt(0)
; __device__ __forceinline__ void scan_phase(LAS unsigned char* lds, const bf16_t* R, const bf16_t* Kb, const bf16_t* V, const bf16_t* WA, const float* k_k, const float* k_a, bf16_t* Y, int G, int bid, int tid) {
;     ...
;         if (producer1) { CK_LOAD(A, pta, 0); CK_LOAD(B, ptb, 0); CK_P1(A, pta, 0); CK_P1(B, ptb, 0); CK_LOAD(A, pta, 1); CK_LOAD(B, ptb, 1); }
; __device__ __forceinline__ void gn_phase(bf16_t* Y, const bf16_t* R, const bf16_t* Kb, const bf16_t* V, const bf16_t* Z, const bf16_t* WA, const float* k_a, const float* r_k, const float* gn_g, const float* gn_b, int G, int bid, int tid) {
;     ...
;         for (int q = 0; q < 4; ++q) {
;             s += (y[q].x + y[q].y) + (y[q].z + y[q].w);
;             const f32x4 kp = k[q] * (1.0f + (aa[q] - 1.0f) * kaq[q]);
;             const f32x4 t = r[q] * kp * rkq[q];
;             bs += (t.x + t.y) + (t.z + t.w);
	v_lshlrev_b32_e32 v28, 16, v14
	v_and_b32_e32 v29, 0xffff0000, v14
	v_lshlrev_b32_e32 v30, 16, v15
	v_and_b32_e32 v31, 0xffff0000, v15
	v_pk_mul_f32 v[50:51], v[8:9], v[28:29]
	v_pk_mul_f32 v[52:53], v[10:11], v[30:31]
	v_lshlrev_b32_e32 v46, 16, v20
	v_and_b32_e32 v47, 0xffff0000, v20
	v_lshlrev_b32_e32 v48, 16, v21
	v_and_b32_e32 v49, 0xffff0000, v21
	v_lshlrev_b32_e32 v24, 16, v18
	v_and_b32_e32 v25, 0xffff0000, v18
	v_lshlrev_b32_e32 v26, 16, v19
	v_and_b32_e32 v27, 0xffff0000, v19
	v_pk_mul_f32 v[18:19], v[52:53], v[52:53]
	v_pk_mul_f32 v[20:21], v[50:51], v[50:51]
	v_lshlrev_b32_e32 v14, 16, v16
	v_pk_mov_b32 v[54:55], v[20:21], v[18:19] op_sel:[1,0]
	v_mov_b32_e32 v21, v19
	v_pk_add_f32 v[36:37], v[54:55], v[20:21]
	v_pk_add_f32 v[18:19], v[48:49], -1.0 op_sel_hi:[1,0]
	v_pk_add_f32 v[20:21], v[46:47], -1.0 op_sel_hi:[1,0]
	v_pk_fma_f32 v[18:19], v[6:7], v[18:19], 1.0 op_sel_hi:[1,1,0]
	v_pk_fma_f32 v[38:39], v[4:5], v[20:21], 1.0 op_sel_hi:[1,1,0]
	v_and_b32_e32 v15, 0xffff0000, v16
	v_lshlrev_b32_e32 v16, 16, v17
	v_and_b32_e32 v17, 0xffff0000, v17
	v_pk_mul_f32 v[20:21], v[18:19], v[30:31]
	v_pk_mul_f32 v[18:19], v[38:39], v[28:29]
	v_lshlrev_b32_e32 v28, 16, v32
	v_and_b32_e32 v29, 0xffff0000, v32
	v_lshlrev_b32_e32 v30, 16, v33
	v_and_b32_e32 v31, 0xffff0000, v33
	ds_write_b128 v101, v[18:21] offset:53248
	ds_write_b128 v101, v[14:17] offset:57344
	v_pk_mul_f32 v[218:219], v[14:15], v[18:19]
	v_pk_mul_f32 v[220:221], v[16:17], v[20:21]
	v_pk_mul_f32 v[218:219], v[218:219], v[208:209]
	v_pk_mul_f32 v[220:221], v[220:221], v[210:211]
	v_pk_add_f32 v[218:219], v[218:219], v[220:221]
	s_nop 0
	v_add_f32_e32 v218, v218, v219
	s_nop 1
	v_add_f32_dpp v218, v218, v218 quad_perm:[1,0,3,2] row_mask:0xf bank_mask:0xf
	s_nop 1
	v_add_f32_dpp v218, v218, v218 quad_perm:[2,3,0,1] row_mask:0xf bank_mask:0xf
	s_nop 1
	v_add_f32_dpp v218, v218, v218 row_half_mirror row_mask:0xf bank_mask:0xf
	s_nop 1
	v_add_f32_dpp v218, v218, v218 row_mirror row_mask:0xf bank_mask:0xf
	global_store_dword v[214:215], v218, off
	ds_write_b32 v22, v1 offset:61440
	ds_write_b128 v101, v[24:27] offset:31744
	v_lshlrev_b32_e32 v32, 16, v42
	v_and_b32_e32 v33, 0xffff0000, v42
	v_lshlrev_b32_e32 v38, 16, v43
	v_and_b32_e32 v39, 0xffff0000, v43
	v_lshlrev_b32_e32 v14, 16, v40
	v_and_b32_e32 v15, 0xffff0000, v40
	v_lshlrev_b32_e32 v16, 16, v41
	v_and_b32_e32 v17, 0xffff0000, v41
	v_pk_mul_f32 v[40:41], v[8:9], v[28:29]
	v_pk_mul_f32 v[42:43], v[10:11], v[30:31]
	v_pk_mul_f32 v[24:25], v[40:41], v[40:41]
	v_pk_mul_f32 v[20:21], v[42:43], v[42:43]
	v_lshlrev_b32_e32 v18, 16, v34
	v_pk_mov_b32 v[26:27], v[24:25], v[20:21] op_sel:[1,0]
	v_mov_b32_e32 v25, v21
	v_pk_add_f32 v[20:21], v[26:27], v[24:25]
	v_mov_b32_e32 v25, v36
	v_mov_b32_e32 v24, v20
	v_mov_b32_e32 v36, v21
	v_pk_add_f32 v[20:21], v[24:25], v[36:37]
	v_and_b32_e32 v19, 0xffff0000, v34
	s_nop 0
	v_mov_b32_dpp v25, v21 quad_perm:[1,0,3,2] row_mask:0xf bank_mask:0xf bound_ctrl:1
	v_mov_b32_dpp v24, v20 quad_perm:[1,0,3,2] row_mask:0xf bank_mask:0xf bound_ctrl:1
	v_pk_add_f32 v[20:21], v[20:21], v[24:25]
	s_nop 1
	v_mov_b32_dpp v25, v21 quad_perm:[2,3,0,1] row_mask:0xf bank_mask:0xf bound_ctrl:1
	v_mov_b32_dpp v24, v20 quad_perm:[2,3,0,1] row_mask:0xf bank_mask:0xf bound_ctrl:1
	v_pk_add_f32 v[20:21], v[20:21], v[24:25]
	s_nop 1
	v_mov_b32_dpp v25, v21 row_half_mirror row_mask:0xf bank_mask:0xf bound_ctrl:1
	v_mov_b32_dpp v24, v20 row_half_mirror row_mask:0xf bank_mask:0xf bound_ctrl:1
	v_pk_add_f32 v[20:21], v[20:21], v[24:25]
	s_nop 1
	v_mov_b32_dpp v25, v21 row_mirror row_mask:0xf bank_mask:0xf bound_ctrl:1
	v_mov_b32_dpp v24, v20 row_mirror row_mask:0xf bank_mask:0xf bound_ctrl:1
	v_pk_add_f32 v[36:37], v[20:21], v[24:25]
	v_lshlrev_b32_e32 v20, 16, v35
	v_rsq_f32_e32 v1, v37
	v_cmp_lt_f32_e32 vcc, s74, v37
	v_and_b32_e32 v21, 0xffff0000, v35
	s_nop 0
	v_cndmask_b32_e32 v24, v183, v1, vcc
	v_rsq_f32_e32 v1, v36
	v_pk_mul_f32 v[26:27], v[52:53], v[24:25] op_sel_hi:[1,0] neg_lo:[0,1] neg_hi:[0,1]
	v_pk_mul_f32 v[24:25], v[50:51], v[24:25] op_sel_hi:[1,0] neg_lo:[0,1] neg_hi:[0,1]
	ds_write_b128 v101, v[24:27] offset:45056
	v_pk_mul_f32 v[26:27], v[26:27], v[48:49] neg_lo:[1,0] neg_hi:[1,0]
	v_pk_mul_f32 v[24:25], v[24:25], v[46:47] neg_lo:[1,0] neg_hi:[1,0]
	v_cmp_lt_f32_e32 vcc, s74, v36
	ds_write_b128 v101, v[24:27] offset:49152
	s_nop 0
	v_cndmask_b32_e32 v24, v183, v1, vcc
	v_pk_mul_f32 v[26:27], v[42:43], v[24:25] op_sel_hi:[1,0] neg_lo:[0,1] neg_hi:[0,1]
	v_pk_mul_f32 v[24:25], v[40:41], v[24:25] op_sel_hi:[1,0] neg_lo:[0,1] neg_hi:[0,1]
	ds_write_b128 v111, v[24:27] offset:45056
	v_pk_mul_f32 v[26:27], v[26:27], v[38:39] neg_lo:[1,0] neg_hi:[1,0]
	v_pk_mul_f32 v[24:25], v[24:25], v[32:33] neg_lo:[1,0] neg_hi:[1,0]
	ds_write_b128 v111, v[24:27] offset:49152
	v_pk_add_f32 v[24:25], v[38:39], -1.0 op_sel_hi:[1,0]
	v_pk_add_f32 v[26:27], v[32:33], -1.0 op_sel_hi:[1,0]
	v_pk_fma_f32 v[24:25], v[6:7], v[24:25], 1.0 op_sel_hi:[1,1,0]
	v_pk_fma_f32 v[32:33], v[4:5], v[26:27], 1.0 op_sel_hi:[1,1,0]
	v_pk_mul_f32 v[26:27], v[24:25], v[30:31]
	v_pk_mul_f32 v[24:25], v[32:33], v[28:29]
	ds_write_b128 v111, v[24:27] offset:53248
	ds_write_b128 v111, v[18:21] offset:57344
	v_pk_mul_f32 v[218:219], v[18:19], v[24:25]
	v_pk_mul_f32 v[220:221], v[20:21], v[26:27]
	v_pk_mul_f32 v[218:219], v[218:219], v[208:209]
	v_pk_mul_f32 v[220:221], v[220:221], v[210:211]
	v_pk_add_f32 v[218:219], v[218:219], v[220:221]
	s_nop 0
	v_add_f32_e32 v218, v218, v219
	s_nop 1
	v_add_f32_dpp v218, v218, v218 quad_perm:[1,0,3,2] row_mask:0xf bank_mask:0xf
	s_nop 1
	v_add_f32_dpp v218, v218, v218 quad_perm:[2,3,0,1] row_mask:0xf bank_mask:0xf
	s_nop 1
	v_add_f32_dpp v218, v218, v218 row_half_mirror row_mask:0xf bank_mask:0xf
	s_nop 1
	v_add_f32_dpp v218, v218, v218 row_mirror row_mask:0xf bank_mask:0xf
	global_store_dword v[214:215], v218, off offset:512
	ds_write_b32 v184, v23 offset:61440
	ds_write_b128 v111, v[14:17] offset:31744
	s_branch .LBB0_884

; __device__ __forceinline__ void gn_phase(bf16_t* Y, const bf16_t* R, const bf16_t* Kb, const bf16_t* V, const bf16_t* Z, const bf16_t* WA, const float* k_a, const float* r_k, const float* gn_g, const float* gn_b, int G, int bid, int tid) {
;     ...
;         for (int q = 0; q < 4; ++q) {
;             s += (y[q].x + y[q].y) + (y[q].z + y[q].w);
;             const f32x4 kp = k[q] * (1.0f + (aa[q] - 1.0f) * kaq[q]);
;             const f32x4 t = r[q] * kp * rkq[q];
;             bs += (t.x + t.y) + (t.z + t.w);
.LBB0_884:
	s_and_b64 vcc, exec, s[52:53]
	s_waitcnt vmcnt(0) lgkmcnt(0)
	s_barrier
	s_cbranch_vccnz .LBB0_886
	v_lshlrev_b32_e32 v28, 16, v134
	v_and_b32_e32 v29, 0xffff0000, v134
	v_lshlrev_b32_e32 v30, 16, v135
	v_and_b32_e32 v31, 0xffff0000, v135
	v_pk_mul_f32 v[36:37], v[8:9], v[28:29]
	v_pk_mul_f32 v[38:39], v[10:11], v[30:31]
	v_pk_mul_f32 v[42:43], v[36:37], v[36:37]
	v_pk_mul_f32 v[40:41], v[38:39], v[38:39]
	v_lshlrev_b32_e32 v32, 16, v140
	v_and_b32_e32 v33, 0xffff0000, v140
	v_lshlrev_b32_e32 v34, 16, v141
	v_and_b32_e32 v35, 0xffff0000, v141
	v_pk_mov_b32 v[44:45], v[42:43], v[40:41] op_sel:[1,0]
	v_mov_b32_e32 v43, v41
	v_pk_add_f32 v[40:41], v[44:45], v[42:43]
	v_pk_add_f32 v[42:43], v[34:35], -1.0 op_sel_hi:[1,0]
	v_pk_add_f32 v[44:45], v[32:33], -1.0 op_sel_hi:[1,0]
	v_pk_fma_f32 v[42:43], v[6:7], v[42:43], 1.0 op_sel_hi:[1,1,0]
	v_pk_fma_f32 v[44:45], v[4:5], v[44:45], 1.0 op_sel_hi:[1,1,0]
	v_pk_mul_f32 v[30:31], v[42:43], v[30:31]
	v_pk_mul_f32 v[28:29], v[44:45], v[28:29]
	v_lshlrev_b32_e32 v24, 16, v136
	v_and_b32_e32 v25, 0xffff0000, v136
	v_lshlrev_b32_e32 v26, 16, v137
	v_and_b32_e32 v27, 0xffff0000, v137
	ds_write_b128 v176, v[28:31] offset:8192
	ds_write_b128 v176, v[24:27] offset:12288
	v_pk_mul_f32 v[218:219], v[24:25], v[28:29]
	v_pk_mul_f32 v[220:221], v[26:27], v[30:31]
	v_pk_mul_f32 v[218:219], v[218:219], v[208:209]
	v_pk_mul_f32 v[220:221], v[220:221], v[210:211]
	v_pk_add_f32 v[218:219], v[218:219], v[220:221]
	s_nop 0
	v_add_f32_e32 v218, v218, v219
	s_nop 1
	v_add_f32_dpp v218, v218, v218 quad_perm:[1,0,3,2] row_mask:0xf bank_mask:0xf
	s_nop 1
	v_add_f32_dpp v218, v218, v218 quad_perm:[2,3,0,1] row_mask:0xf bank_mask:0xf
	s_nop 1
	v_add_f32_dpp v218, v218, v218 row_half_mirror row_mask:0xf bank_mask:0xf
	s_nop 1
	v_add_f32_dpp v218, v218, v218 row_mirror row_mask:0xf bank_mask:0xf
	global_store_dword v[214:215], v218, off offset:1024
	v_lshlrev_b32_e32 v30, 16, v126
	v_and_b32_e32 v31, 0xffff0000, v126
	v_lshlrev_b32_e32 v42, 16, v127
	v_and_b32_e32 v43, 0xffff0000, v127
	v_pk_mul_f32 v[48:49], v[8:9], v[30:31]
	v_pk_mul_f32 v[50:51], v[10:11], v[42:43]
	v_pk_mul_f32 v[28:29], v[48:49], v[48:49]
	v_pk_mul_f32 v[26:27], v[50:51], v[50:51]
	s_lshl_b64 s[62:63], s[78:79], 1
	v_pk_mov_b32 v[52:53], v[28:29], v[26:27] op_sel:[1,0]
	v_mov_b32_e32 v29, v27
	v_pk_add_f32 v[26:27], v[52:53], v[28:29]
	v_mov_b32_e32 v29, v40
	v_mov_b32_e32 v28, v26
	v_mov_b32_e32 v40, v27
	v_pk_add_f32 v[26:27], v[28:29], v[40:41]
	s_add_u32 s80, s66, s62
	s_addc_u32 s81, s67, s63
	v_mov_b32_dpp v29, v27 quad_perm:[1,0,3,2] row_mask:0xf bank_mask:0xf bound_ctrl:1
	v_mov_b32_dpp v28, v26 quad_perm:[1,0,3,2] row_mask:0xf bank_mask:0xf bound_ctrl:1
	v_pk_add_f32 v[26:27], v[26:27], v[28:29]
	s_lshl_b64 s[52:53], s[60:61], 1
	s_add_u32 s52, s80, s52
	v_mov_b32_dpp v29, v27 quad_perm:[2,3,0,1] row_mask:0xf bank_mask:0xf bound_ctrl:1
	v_mov_b32_dpp v28, v26 quad_perm:[2,3,0,1] row_mask:0xf bank_mask:0xf bound_ctrl:1
	v_pk_add_f32 v[26:27], v[26:27], v[28:29]
	s_addc_u32 s53, s81, s53
	v_mov_b32_e32 v13, v0
	v_mov_b32_dpp v29, v27 row_half_mirror row_mask:0xf bank_mask:0xf bound_ctrl:1
	v_mov_b32_dpp v28, v26 row_half_mirror row_mask:0xf bank_mask:0xf bound_ctrl:1
	v_pk_add_f32 v[26:27], v[26:27], v[28:29]
	v_add_u32_e32 v1, 0x13400, v22
	v_lshl_add_u64 v[16:17], s[52:53], 0, v[12:13]
	v_mov_b32_dpp v29, v27 row_mirror row_mask:0xf bank_mask:0xf bound_ctrl:1
	v_mov_b32_dpp v28, v26 row_mirror row_mask:0xf bank_mask:0xf bound_ctrl:1
	v_pk_add_f32 v[40:41], v[26:27], v[28:29]
	v_lshlrev_b32_e32 v12, 16, v138
	v_and_b32_e32 v13, 0xffff0000, v138
	v_lshlrev_b32_e32 v14, 16, v139
	v_and_b32_e32 v15, 0xffff0000, v139
	ds_write_b32 v1, v187
	ds_write_b128 v101, v[12:15] offset:35840
	v_rsq_f32_e32 v1, v41
	v_cmp_lt_f32_e64 s[52:53], s74, v41
	v_cmp_lt_f32_e32 vcc, s74, v40
	v_lshlrev_b32_e32 v44, 16, v132
; __device__ __forceinline__ void scan_phase(LAS unsigned char* lds, const bf16_t* R, const bf16_t* Kb, const bf16_t* V, const bf16_t* WA, const float* k_k, const float* k_a, bf16_t* Y, int G, int bid, int tid) {
;     ...
;         if (producer1) { CK_LOAD(A, pta, 0); CK_LOAD(B, ptb, 0); CK_P1(A, pta, 0); CK_P1(B, ptb, 0); CK_LOAD(A, pta, 1); CK_LOAD(B, ptb, 1); }
;         f32x4 H[4];
; #pragma unroll
;         for (int kt = 0; kt < 4; ++kt) H[kt] = (f32x4){0.f, 0.f, 0.f, 0.f};
;         __syncthreads();
;         for (int it = 0; it <= NCH; ++it) {
;             if (producer1 && it + 1 < NCH) { CK_P1(A, pta, it + 1); CK_P1(B, ptb, it + 1); if (it + 2 < NCH) { CK_LOAD(A, pta, it + 2); CK_LOAD(B, ptb, it + 2); } }
	v_cndmask_b32_e64 v26, v183, v1, s[52:53]
	v_rsq_f32_e32 v1, v40
	v_pk_mul_f32 v[28:29], v[38:39], v[26:27] op_sel_hi:[1,0] neg_lo:[0,1] neg_hi:[0,1]
	v_pk_mul_f32 v[26:27], v[36:37], v[26:27] op_sel_hi:[1,0] neg_lo:[0,1] neg_hi:[0,1]
	ds_write_b128 v101, v[26:29] offset:62464
	v_pk_mul_f32 v[28:29], v[28:29], v[34:35] neg_lo:[1,0] neg_hi:[1,0]
	v_pk_mul_f32 v[26:27], v[26:27], v[32:33] neg_lo:[1,0] neg_hi:[1,0]
	ds_write_b128 v176, v[26:29] offset:4096
	v_cndmask_b32_e32 v26, v183, v1, vcc
	v_and_b32_e32 v45, 0xffff0000, v132
	v_lshlrev_b32_e32 v46, 16, v133
	v_and_b32_e32 v47, 0xffff0000, v133
	v_pk_mul_f32 v[28:29], v[50:51], v[26:27] op_sel_hi:[1,0] neg_lo:[0,1] neg_hi:[0,1]
	v_pk_mul_f32 v[26:27], v[48:49], v[26:27] op_sel_hi:[1,0] neg_lo:[0,1] neg_hi:[0,1]
	ds_write_b128 v111, v[26:29] offset:62464
	v_pk_mul_f32 v[28:29], v[28:29], v[46:47] neg_lo:[1,0] neg_hi:[1,0]
	v_pk_mul_f32 v[26:27], v[26:27], v[44:45] neg_lo:[1,0] neg_hi:[1,0]
	ds_write_b128 v177, v[26:29] offset:4096
	v_pk_add_f32 v[26:27], v[46:47], -1.0 op_sel_hi:[1,0]
	v_pk_add_f32 v[28:29], v[44:45], -1.0 op_sel_hi:[1,0]
	v_pk_fma_f32 v[26:27], v[6:7], v[26:27], 1.0 op_sel_hi:[1,1,0]
	v_pk_fma_f32 v[32:33], v[4:5], v[28:29], 1.0 op_sel_hi:[1,1,0]
	v_lshlrev_b32_e32 v12, 16, v130
	v_and_b32_e32 v13, 0xffff0000, v130
	v_pk_mul_f32 v[28:29], v[26:27], v[42:43]
	v_pk_mul_f32 v[26:27], v[32:33], v[30:31]
	s_or_b32 s0, s0, 32
	v_lshlrev_b32_e32 v14, 16, v131
	v_and_b32_e32 v15, 0xffff0000, v131
	v_lshlrev_b32_e32 v22, 16, v128
	v_and_b32_e32 v23, 0xffff0000, v128
	v_lshlrev_b32_e32 v24, 16, v129
	v_and_b32_e32 v25, 0xffff0000, v129
	ds_write_b128 v177, v[26:29] offset:8192
	ds_write_b128 v177, v[22:25] offset:12288
	v_pk_mul_f32 v[218:219], v[22:23], v[26:27]
	v_pk_mul_f32 v[220:221], v[24:25], v[28:29]
	v_pk_mul_f32 v[218:219], v[218:219], v[208:209]
	v_pk_mul_f32 v[220:221], v[220:221], v[210:211]
	v_pk_add_f32 v[218:219], v[218:219], v[220:221]
	s_nop 0
	v_add_f32_e32 v218, v218, v219
	s_nop 1
	v_add_f32_dpp v218, v218, v218 quad_perm:[1,0,3,2] row_mask:0xf bank_mask:0xf
	s_nop 1
	v_add_f32_dpp v218, v218, v218 quad_perm:[2,3,0,1] row_mask:0xf bank_mask:0xf
	s_nop 1
	v_add_f32_dpp v218, v218, v218 row_half_mirror row_mask:0xf bank_mask:0xf
	s_nop 1
	v_add_f32_dpp v218, v218, v218 row_mirror row_mask:0xf bank_mask:0xf
	global_store_dword v[214:215], v218, off offset:1536
	ds_write_b32 v185, v186
	ds_write_b128 v111, v[12:15] offset:35840
	v_mov_b32_e32 v13, s1
	v_or_b32_e32 v12, s0, v98
	v_lshlrev_b64 v[14:15], 11, v[12:13]
	v_lshlrev_b64 v[12:13], 12, v[12:13]
	v_lshl_add_u64 v[20:21], v[112:113], 0, s[62:63]
	v_lshl_add_u64 v[12:13], s[68:69], 0, v[12:13]
	v_lshl_add_u64 v[18:19], v[114:115], 0, s[62:63]
	v_lshl_add_u64 v[22:23], v[20:21], 0, v[14:15]
	v_lshl_add_u64 v[12:13], v[12:13], 0, s[62:63]
	v_mov_b32_e32 v3, v0
	global_load_dwordx2 v[188:189], v[22:23], off
	v_lshl_add_u64 v[22:23], v[18:19], 0, v[14:15]
	v_lshl_add_u64 v[12:13], v[12:13], 0, v[2:3]
	global_load_dwordx2 v[190:191], v[22:23], off
	global_load_dwordx2 v[192:193], v[12:13], off
	global_load_dwordx2 v[194:195], v[12:13], off offset:2048
	v_lshl_add_u64 v[12:13], v[16:17], 0, v[14:15]
	global_load_dword v196, v[12:13], off
	v_mov_b32_e32 v13, s1
	v_or_b32_e32 v12, s0, v100
	v_lshlrev_b64 v[14:15], 11, v[12:13]
	v_lshlrev_b64 v[12:13], 12, v[12:13]
	v_lshl_add_u64 v[12:13], s[68:69], 0, v[12:13]
	v_lshl_add_u64 v[12:13], v[12:13], 0, s[62:63]
	v_lshl_add_u64 v[20:21], v[20:21], 0, v[14:15]
	v_lshl_add_u64 v[18:19], v[18:19], 0, v[14:15]
	v_lshl_add_u64 v[2:3], v[12:13], 0, v[2:3]
	global_load_dwordx2 v[198:199], v[20:21], off
	global_load_dwordx2 v[200:201], v[18:19], off
	global_load_dwordx2 v[202:203], v[2:3], off
	global_load_dwordx2 v[204:205], v[2:3], off offset:2048
	v_lshl_add_u64 v[2:3], v[16:17], 0, v[14:15]
	global_load_dword v197, v[2:3], off

; __device__ __forceinline__ void gn_phase(bf16_t* Y, const bf16_t* R, const bf16_t* Kb, const bf16_t* V, const bf16_t* Z, const bf16_t* WA, const float* k_a, const float* r_k, const float* gn_g, const float* gn_b, int G, int bid, int tid) {
;     ...
;         for (int q = 0; q < 4; ++q) {
;             s += (y[q].x + y[q].y) + (y[q].z + y[q].w);
;             const f32x4 kp = k[q] * (1.0f + (aa[q] - 1.0f) * kaq[q]);
;             const f32x4 t = r[q] * kp * rkq[q];
;             bs += (t.x + t.y) + (t.z + t.w);
.Lmy_p1_noload:
	v_lshlrev_b32_e32 v2, 16, v134
	v_and_b32_e32 v3, 0xffff0000, v134
	v_lshlrev_b32_e32 v36, 16, v135
	v_and_b32_e32 v37, 0xffff0000, v135
	v_pk_mul_f32 v[44:45], v[8:9], v[2:3]
	v_pk_mul_f32 v[46:47], v[10:11], v[36:37]
	v_pk_mul_f32 v[48:49], v[44:45], v[44:45]
	v_pk_mul_f32 v[38:39], v[46:47], v[46:47]
	v_lshlrev_b32_e32 v40, 16, v140
	v_and_b32_e32 v41, 0xffff0000, v140
	v_lshlrev_b32_e32 v42, 16, v141
	v_and_b32_e32 v43, 0xffff0000, v141
	v_pk_mov_b32 v[50:51], v[48:49], v[38:39] op_sel:[1,0]
	v_mov_b32_e32 v49, v39
	s_andn2_b32 s0, 1, s62
	v_pk_add_f32 v[48:49], v[50:51], v[48:49]
	s_mul_i32 s1, s0, 0x4400
	v_pk_add_f32 v[38:39], v[42:43], -1.0 op_sel_hi:[1,0]
	v_pk_add_f32 v[50:51], v[40:41], -1.0 op_sel_hi:[1,0]
	s_add_i32 s1, s1, 0
	v_pk_fma_f32 v[50:51], v[4:5], v[50:51], 1.0 op_sel_hi:[1,1,0]
	v_pk_fma_f32 v[38:39], v[6:7], v[38:39], 1.0 op_sel_hi:[1,1,0]
	s_mulk_i32 s0, 0xcc00
	v_add_u32_e32 v1, s1, v99
	v_pk_mul_f32 v[38:39], v[38:39], v[36:37]
	v_pk_mul_f32 v[36:37], v[50:51], v[2:3]
	v_add_u32_e32 v2, s1, v103
	s_add_i32 s0, s1, s0
	v_lshlrev_b32_e32 v28, 16, v138
	v_and_b32_e32 v29, 0xffff0000, v138
	v_lshlrev_b32_e32 v30, 16, v139
	v_and_b32_e32 v31, 0xffff0000, v139
	v_lshlrev_b32_e32 v32, 16, v136
	v_and_b32_e32 v33, 0xffff0000, v136
	v_lshlrev_b32_e32 v34, 16, v137
	v_and_b32_e32 v35, 0xffff0000, v137
	ds_write_b128 v1, v[36:39] offset:53248
	ds_write_b128 v1, v[32:35] offset:57344
	v_pk_mul_f32 v[218:219], v[32:33], v[36:37]
	v_pk_mul_f32 v[220:221], v[34:35], v[38:39]
	v_pk_mul_f32 v[218:219], v[218:219], v[208:209]
	v_pk_mul_f32 v[220:221], v[220:221], v[210:211]
	v_pk_add_f32 v[218:219], v[218:219], v[220:221]
	s_nop 0
	v_add_f32_e32 v218, v218, v219
	s_nop 1
	v_add_f32_dpp v218, v218, v218 quad_perm:[1,0,3,2] row_mask:0xf bank_mask:0xf
	s_nop 1
	v_add_f32_dpp v218, v218, v218 quad_perm:[2,3,0,1] row_mask:0xf bank_mask:0xf
	s_nop 1
	v_add_f32_dpp v218, v218, v218 row_half_mirror row_mask:0xf bank_mask:0xf
	s_nop 1
	v_add_f32_dpp v218, v218, v218 row_mirror row_mask:0xf bank_mask:0xf
	s_add_i32 s98, s62, 1
	s_lshl_b32 s98, s98, 10
	v_add_co_u32_e32 v216, vcc, s98, v214
	s_nop 1
	v_addc_co_u32_e32 v217, vcc, 0, v215, vcc
	global_store_dword v[216:217], v218, off
	ds_write_b32 v2, v187 offset:61440
	v_add_u32_e32 v2, s0, v99
	ds_write_b128 v2, v[28:31] offset:31744
	v_lshlrev_b32_e32 v2, 16, v126
	v_and_b32_e32 v3, 0xffff0000, v126
	v_lshlrev_b32_e32 v50, 16, v127
	v_and_b32_e32 v51, 0xffff0000, v127
	v_pk_mul_f32 v[56:57], v[8:9], v[2:3]
	v_pk_mul_f32 v[58:59], v[10:11], v[50:51]
	v_pk_mul_f32 v[36:37], v[56:57], v[56:57]
	v_pk_mul_f32 v[34:35], v[58:59], v[58:59]
	v_lshlrev_b32_e32 v52, 16, v132
	v_pk_mov_b32 v[38:39], v[36:37], v[34:35] op_sel:[1,0]
	v_mov_b32_e32 v37, v35
	v_pk_add_f32 v[34:35], v[38:39], v[36:37]
	v_mov_b32_e32 v37, v48
	v_mov_b32_e32 v36, v34
	v_mov_b32_e32 v48, v35
	v_pk_add_f32 v[34:35], v[36:37], v[48:49]
	v_and_b32_e32 v53, 0xffff0000, v132
	v_lshlrev_b32_e32 v54, 16, v133
	v_mov_b32_dpp v37, v35 quad_perm:[1,0,3,2] row_mask:0xf bank_mask:0xf bound_ctrl:1
	v_mov_b32_dpp v36, v34 quad_perm:[1,0,3,2] row_mask:0xf bank_mask:0xf bound_ctrl:1
	v_pk_add_f32 v[34:35], v[34:35], v[36:37]
	v_and_b32_e32 v55, 0xffff0000, v133
	v_lshlrev_b32_e32 v32, 16, v128
	v_mov_b32_dpp v37, v35 quad_perm:[2,3,0,1] row_mask:0xf bank_mask:0xf bound_ctrl:1
	v_mov_b32_dpp v36, v34 quad_perm:[2,3,0,1] row_mask:0xf bank_mask:0xf bound_ctrl:1
	v_pk_add_f32 v[34:35], v[34:35], v[36:37]
	v_and_b32_e32 v33, 0xffff0000, v128
	v_lshlrev_b32_e32 v28, 16, v130
	v_mov_b32_dpp v37, v35 row_half_mirror row_mask:0xf bank_mask:0xf bound_ctrl:1
	v_mov_b32_dpp v36, v34 row_half_mirror row_mask:0xf bank_mask:0xf bound_ctrl:1
	v_pk_add_f32 v[34:35], v[34:35], v[36:37]
	v_and_b32_e32 v29, 0xffff0000, v130
	v_lshlrev_b32_e32 v30, 16, v131
	v_mov_b32_dpp v37, v35 row_mirror row_mask:0xf bank_mask:0xf bound_ctrl:1
	v_mov_b32_dpp v36, v34 row_mirror row_mask:0xf bank_mask:0xf bound_ctrl:1
	v_pk_add_f32 v[48:49], v[34:35], v[36:37]
	v_lshlrev_b32_e32 v34, 16, v129
	v_rsq_f32_e32 v36, v49
	v_cmp_lt_f32_e32 vcc, s74, v49
	v_and_b32_e32 v35, 0xffff0000, v129
	v_and_b32_e32 v31, 0xffff0000, v131
	v_cndmask_b32_e32 v36, v183, v36, vcc
	v_pk_mul_f32 v[38:39], v[46:47], v[36:37] op_sel_hi:[1,0] neg_lo:[0,1] neg_hi:[0,1]
	v_pk_mul_f32 v[36:37], v[44:45], v[36:37] op_sel_hi:[1,0] neg_lo:[0,1] neg_hi:[0,1]
	ds_write_b128 v1, v[36:39] offset:45056
	v_pk_mul_f32 v[38:39], v[38:39], v[42:43] neg_lo:[1,0] neg_hi:[1,0]
	v_rsq_f32_e32 v42, v48
	v_pk_mul_f32 v[36:37], v[36:37], v[40:41] neg_lo:[1,0] neg_hi:[1,0]
	v_cmp_lt_f32_e32 vcc, s74, v48
	ds_write_b128 v1, v[36:39] offset:49152
	v_add_u32_e32 v1, s1, v105
	v_cndmask_b32_e32 v36, v183, v42, vcc
	v_pk_mul_f32 v[38:39], v[58:59], v[36:37] op_sel_hi:[1,0] neg_lo:[0,1] neg_hi:[0,1]
	v_pk_mul_f32 v[36:37], v[56:57], v[36:37] op_sel_hi:[1,0] neg_lo:[0,1] neg_hi:[0,1]
	ds_write_b128 v1, v[36:39] offset:45056
	v_pk_mul_f32 v[38:39], v[38:39], v[54:55] neg_lo:[1,0] neg_hi:[1,0]
	v_pk_mul_f32 v[36:37], v[36:37], v[52:53] neg_lo:[1,0] neg_hi:[1,0]
	ds_write_b128 v1, v[36:39] offset:49152
	v_pk_add_f32 v[36:37], v[54:55], -1.0 op_sel_hi:[1,0]
	v_pk_add_f32 v[38:39], v[52:53], -1.0 op_sel_hi:[1,0]
	v_pk_fma_f32 v[36:37], v[6:7], v[36:37], 1.0 op_sel_hi:[1,1,0]
	v_pk_fma_f32 v[40:41], v[4:5], v[38:39], 1.0 op_sel_hi:[1,1,0]
	v_pk_mul_f32 v[38:39], v[36:37], v[50:51]
	v_pk_mul_f32 v[36:37], v[40:41], v[2:3]
	ds_write_b128 v1, v[36:39] offset:53248
	ds_write_b128 v1, v[32:35] offset:57344
	v_pk_mul_f32 v[218:219], v[32:33], v[36:37]
	v_pk_mul_f32 v[220:221], v[34:35], v[38:39]
	v_pk_mul_f32 v[218:219], v[218:219], v[208:209]
	v_pk_mul_f32 v[220:221], v[220:221], v[210:211]
	v_pk_add_f32 v[218:219], v[218:219], v[220:221]
	s_nop 0
	v_add_f32_e32 v218, v218, v219
	s_nop 1
	v_add_f32_dpp v218, v218, v218 quad_perm:[1,0,3,2] row_mask:0xf bank_mask:0xf
	s_nop 1
	v_add_f32_dpp v218, v218, v218 quad_perm:[2,3,0,1] row_mask:0xf bank_mask:0xf
	s_nop 1
	v_add_f32_dpp v218, v218, v218 row_half_mirror row_mask:0xf bank_mask:0xf
	s_nop 1
	v_add_f32_dpp v218, v218, v218 row_mirror row_mask:0xf bank_mask:0xf
	s_add_i32 s98, s62, 1
	s_lshl_b32 s98, s98, 10
	v_add_co_u32_e32 v216, vcc, s98, v214
	s_nop 1
	v_addc_co_u32_e32 v217, vcc, 0, v215, vcc
	global_store_dword v[216:217], v218, off offset:512
	v_add3_u32 v1, s1, v155, v102
	ds_write_b32 v1, v186 offset:61440
	v_add_u32_e32 v1, s0, v105
	ds_write_b128 v1, v[28:31] offset:31744

; #define LAS __attribute__((address_space(3)))
; __device__ __forceinline__ void scan_phase(LAS unsigned char* lds, const bf16_t* R, const bf16_t* Kb, const bf16_t* V, const bf16_t* WA, const float* k_k, const float* k_a, bf16_t* Y, int G, int bid, int tid) {
;     ...
;                 f32x4 xab = (f32x4){0.f, 0.f, 0.f, 0.f}, xak = xab, xrb = xab, xrk = xab;
;                 bf16x8 pa[2], pr[2];
; #pragma unroll
;                 for (int ks = 0; ks < 2; ++ks) {
;                     const LAS unsigned char* rp = buf + c * CK_RP + 64 * ks + 16 * g;
;                     pa[ks] = *(const LAS bf16x8*)(rp + CK_ABAR); pr[ks] = *(const LAS bf16x8*)(rp + CK_RBAR);
;                     const bf16x8 pb = *(const LAS bf16x8*)(rp + CK_BTIL), pk = *(const LAS bf16x8*)(rp + CK_KTIL);
;                     xab = CK_MFMA(pb, pa[ks], xab); xak = CK_MFMA(pk, pa[ks], xak); xrb = CK_MFMA(pb, pr[ks], xrb); xrk = CK_MFMA(pk, pr[ks], xrk);
;                 }
; #pragma unroll
;                 for (int r = 0; r < 4; ++r) { const int s = 4 * g + r; if (!(s < c)) { xab[r] = 0.f; xak[r] = 0.f; } if (!(s <= c)) { xrb[r] = 0.f; xrk[r] = 0.f; } }
; #pragma unroll
;                 for (int r = 0; r < 4; ++r) AabT[(4 * g + r) * 16 + c] = xab[r];
;                 const bf16x8 opak = ck_pk4(xak), oprb = ck_pk4(xrb), oprk = ck_pk4(xrk);
;                 bf16x8 oph[2];
; #pragma unroll
;                 for (int ks = 0; ks < 2; ++ks) oph[ks] = __builtin_bit_cast(bf16x8, (u32x4){ck_cvt(H[2 * ks][0], H[2 * ks][1]), ck_cvt(H[2 * ks][2], H[2 * ks][3]), ck_cvt(H[2 * ks + 1][0], H[2 * ks + 1][1]), ck_cvt(H[2 * ks + 1][2], H[2 * ks + 1][3])});
;                 const bf16x8 opv = ck_ld1(buf + CK_VT + (wave * 16 + c) * CK_TP + g * 8);
;                 f32x4 rhs = (f32x4){0.f, 0.f, 0.f, 0.f};
;                 rhs = CK_MFMA(pa[0], oph[0], rhs); rhs = CK_MFMA(pa[1], oph[1], rhs); rhs = CK_MFMA(opak, opv, rhs);
;                 float u[16];
; #pragma unroll
;                 for (int r = 0; r < 4; ++r) {
;                     const unsigned a_ = __float_as_uint(rhs[r]);
;                     const auto h_ = __builtin_amdgcn_permlane32_swap(a_, a_, false, false);
;                     const auto lo_ = __builtin_amdgcn_permlane16_swap(h_[0], h_[0], false, false);
;                     const auto hi_ = __builtin_amdgcn_permlane16_swap(h_[1], h_[1], false, false);
.Lmy_help_body:
	s_and_b32 s1, s63, 1
	s_lshl_b32 s1, s1, 12
	s_and_b32 s0, s63, 3
	s_mul_i32 s0, s0, 0x3e00
	s_add_i32 s0, s0, 0x14000
	v_add_u32_e32 v88, s0, v170
	v_add_u32_e32 v89, s1, v171
	v_add_u32_e32 v90, s1, v172
	v_add_u32_e32 v91, s1, v174
	ds_read_b128 v[12:15], v88 offset:4608
	ds_read_b128 v[28:31], v88 offset:0
	ds_read_b128 v[16:19], v88 offset:4672
	ds_read_b128 v[32:35], v88 offset:64
	ds_read_b128 v[20:23], v88 offset:6912
	ds_read_b128 v[24:27], v88 offset:6976
	ds_read_b128 v[36:39], v88 offset:2304
	ds_read_b128 v[40:43], v88 offset:2368
	s_waitcnt lgkmcnt(6)
	v_mfma_f32_16x16x32_bf16 v[232:235], v[12:15], v[28:31], 0
	s_waitcnt lgkmcnt(4)
	v_mfma_f32_16x16x32_bf16 v[232:235], v[16:19], v[32:35], v[232:235]
	s_waitcnt lgkmcnt(2)
	v_mfma_f32_16x16x32_bf16 v[236:239], v[20:23], v[28:31], 0
	v_mfma_f32_16x16x32_bf16 v[236:239], v[24:27], v[32:35], v[236:239]
	s_waitcnt lgkmcnt(0)
	v_mfma_f32_16x16x32_bf16 v[240:243], v[12:15], v[36:39], 0
	v_mfma_f32_16x16x32_bf16 v[244:247], v[20:23], v[36:39], 0
	v_mfma_f32_16x16x32_bf16 v[240:243], v[16:19], v[40:43], v[240:243]
	v_mfma_f32_16x16x32_bf16 v[244:247], v[24:27], v[40:43], v[244:247]
	s_nop 1
	ds_write2_b32 v173, v232, v233 offset1:16
	ds_write2_b32 v173, v234, v235 offset0:32 offset1:48
	ds_read_b128 v[12:15], v175 offset:0
	ds_read_b128 v[16:19], v175 offset:16
	ds_read_b128 v[20:23], v175 offset:32
	ds_read_b128 v[24:27], v175 offset:48
	ds_read_b128 v[28:31], v175 offset:64
	ds_read_b128 v[32:35], v175 offset:80
	ds_read_b128 v[36:39], v175 offset:96
	ds_read_b128 v[40:43], v175 offset:112
	ds_read_b128 v[44:47], v175 offset:128
	ds_read_b128 v[48:51], v175 offset:144
	ds_read_b128 v[52:55], v175 offset:160
	ds_read_b128 v[56:59], v175 offset:176
	v_and_b32_e32 v236, v236, v188
	v_and_b32_e32 v237, v237, v189
	v_and_b32_e32 v238, v238, v190
	v_and_b32_e32 v239, v239, v191
	v_cvt_pk_bf16_f32 v76, v236, v237
	v_cvt_pk_bf16_f32 v77, v238, v239
	v_and_b32_e32 v240, v240, v192
	v_and_b32_e32 v241, v241, v193
	v_and_b32_e32 v242, v242, v194
	v_and_b32_e32 v243, v243, v195
	v_cvt_pk_bf16_f32 v80, v240, v241
	v_cvt_pk_bf16_f32 v81, v242, v243
	v_and_b32_e32 v244, v244, v192
	v_and_b32_e32 v245, v245, v193
	v_and_b32_e32 v246, v246, v194
	v_and_b32_e32 v247, v247, v195
	v_cvt_pk_bf16_f32 v82, v244, v245
	v_cvt_pk_bf16_f32 v83, v246, v247
	s_waitcnt lgkmcnt(8)
	ds_write_b64 v90, v[76:77] offset:1024
	ds_write_b128 v89, v[80:83] offset:2048
	ds_read_b128 v[60:63], v175 offset:208
	ds_read_b128 v[64:67], v175 offset:224
	ds_read_b128 v[68:71], v175 offset:240
	s_waitcnt lgkmcnt(9)
	v_fma_f32 v217, v13, v196, v197
	v_pk_fma_f32 v[218:219], v[14:15], v[196:197], v[198:199] op_sel_hi:[1,0,1]
	v_pk_fma_f32 v[220:221], v[16:17], v[196:197], v[200:201] op_sel_hi:[1,0,1]
	v_pk_fma_f32 v[222:223], v[18:19], v[196:197], v[202:203] op_sel_hi:[1,0,1]
	v_pk_fma_f32 v[224:225], v[20:21], v[196:197], v[204:205] op_sel_hi:[1,0,1]
	v_pk_fma_f32 v[226:227], v[22:23], v[196:197], v[206:207] op_sel_hi:[1,0,1]
	v_pk_fma_f32 v[228:229], v[24:25], v[196:197], v[208:209] op_sel_hi:[1,0,1]
	v_pk_fma_f32 v[230:231], v[26:27], v[196:197], v[210:211] op_sel_hi:[1,0,1]
	ds_read_b128 v[72:75], v175 offset:272
	ds_read_b128 v[12:15], v175 offset:288
	ds_read_b128 v[16:19], v175 offset:304
	s_waitcnt lgkmcnt(8)
	v_pk_fma_f32 v[218:219], v[30:31], v[216:217], v[218:219] op_sel:[0,1,0] op_sel_hi:[1,1,1]
	v_pk_fma_f32 v[220:221], v[32:33], v[216:217], v[220:221] op_sel:[0,1,0] op_sel_hi:[1,1,1]
	v_pk_fma_f32 v[222:223], v[34:35], v[216:217], v[222:223] op_sel:[0,1,0] op_sel_hi:[1,1,1]
	v_pk_fma_f32 v[224:225], v[36:37], v[216:217], v[224:225] op_sel:[0,1,0] op_sel_hi:[1,1,1]
	v_pk_fma_f32 v[226:227], v[38:39], v[216:217], v[226:227] op_sel:[0,1,0] op_sel_hi:[1,1,1]
	v_pk_fma_f32 v[228:229], v[40:41], v[216:217], v[228:229] op_sel:[0,1,0] op_sel_hi:[1,1,1]
	v_pk_fma_f32 v[230:231], v[42:43], v[216:217], v[230:231] op_sel:[0,1,0] op_sel_hi:[1,1,1]
	ds_read_b128 v[20:23], v175 offset:336
	ds_read_b128 v[24:27], v175 offset:352
	ds_read_b128 v[28:31], v175 offset:368
	s_waitcnt lgkmcnt(6)
	v_fmac_f32_e32 v219, v47, v218
	v_pk_fma_f32 v[220:221], v[48:49], v[218:219], v[220:221] op_sel_hi:[1,0,1]
	v_pk_fma_f32 v[222:223], v[50:51], v[218:219], v[222:223] op_sel_hi:[1,0,1]
	v_pk_fma_f32 v[224:225], v[52:53], v[218:219], v[224:225] op_sel_hi:[1,0,1]
	v_pk_fma_f32 v[226:227], v[54:55], v[218:219], v[226:227] op_sel_hi:[1,0,1]
	v_pk_fma_f32 v[228:229], v[56:57], v[218:219], v[228:229] op_sel_hi:[1,0,1]
	v_pk_fma_f32 v[230:231], v[58:59], v[218:219], v[230:231] op_sel_hi:[1,0,1]
	ds_read_b128 v[32:35], v175 offset:400
	ds_read_b128 v[36:39], v175 offset:416
	ds_read_b128 v[40:43], v175 offset:432
	s_waitcnt lgkmcnt(6)
; __device__ __forceinline__ unsigned ck_cvt(float lo, float hi) { const f32x2 v = {lo, hi}; return __builtin_bit_cast(unsigned, __builtin_convertvector(v, ck_bf16x2_t)); }
; #define CK_COLLD(ss) do { _Pragma("unroll") for (int q_ = ((ss) + 1) / 4; q_ < 4; ++q_) cw[(ss)][q_] = *(const LAS f32x4*)(AabT + (ss) * 16 + 4 * q_); } while (0)
; __device__ __forceinline__ void scan_phase(LAS unsigned char* lds, const bf16_t* R, const bf16_t* Kb, const bf16_t* V, const bf16_t* WA, const float* k_k, const float* k_a, bf16_t* Y, int G, int bid, int tid) {
;     ...
;                 for (int s = 0; s < 15; ++s) {
;                     if (s + 2 < 15) CK_COLLD(s + 2);
;                     __builtin_amdgcn_sched_barrier(0);
; #pragma unroll
;                     for (int t = s + 1; t < 16; ++t) u[t] += cw[s][t >> 2][t & 3] * u[s];
;                 }
;     ...
;                 bf16x8 opu;
;                 { const bool g1 = (g & 1) != 0, g2 = (g & 2) != 0;
;                   const float a0 = g1 ? u[4] : u[0], a1 = g1 ? u[5] : u[1], a2 = g1 ? u[6] : u[2], a3 = g1 ? u[7] : u[3];
;                   const float b0 = g1 ? u[12] : u[8], b1 = g1 ? u[13] : u[9], b2 = g1 ? u[14] : u[10], b3 = g1 ? u[15] : u[11];
;                   opu = __builtin_bit_cast(bf16x8, (u32x4){ck_cvt(g2 ? b0 : a0, g2 ? b1 : a1), ck_cvt(g2 ? b2 : a2, g2 ? b3 : a3), 0u, 0u}); }
	v_pk_fma_f32 v[220:221], v[60:61], v[218:219], v[220:221] op_sel:[0,1,0] op_sel_hi:[1,1,1]
	v_pk_fma_f32 v[222:223], v[62:63], v[218:219], v[222:223] op_sel:[0,1,0] op_sel_hi:[1,1,1]
	v_pk_fma_f32 v[224:225], v[64:65], v[218:219], v[224:225] op_sel:[0,1,0] op_sel_hi:[1,1,1]
	v_pk_fma_f32 v[226:227], v[66:67], v[218:219], v[226:227] op_sel:[0,1,0] op_sel_hi:[1,1,1]
	v_pk_fma_f32 v[228:229], v[68:69], v[218:219], v[228:229] op_sel:[0,1,0] op_sel_hi:[1,1,1]
	v_pk_fma_f32 v[230:231], v[70:71], v[218:219], v[230:231] op_sel:[0,1,0] op_sel_hi:[1,1,1]
	ds_read_b128 v[44:47], v175 offset:480
	ds_read_b128 v[48:51], v175 offset:496
	s_waitcnt lgkmcnt(5)
	v_fmac_f32_e32 v221, v73, v220
	v_pk_fma_f32 v[222:223], v[74:75], v[220:221], v[222:223] op_sel_hi:[1,0,1]
	v_pk_fma_f32 v[224:225], v[12:13], v[220:221], v[224:225] op_sel_hi:[1,0,1]
	v_pk_fma_f32 v[226:227], v[14:15], v[220:221], v[226:227] op_sel_hi:[1,0,1]
	v_pk_fma_f32 v[228:229], v[16:17], v[220:221], v[228:229] op_sel_hi:[1,0,1]
	v_pk_fma_f32 v[230:231], v[18:19], v[220:221], v[230:231] op_sel_hi:[1,0,1]
	ds_read_b128 v[52:55], v175 offset:544
	ds_read_b128 v[56:59], v175 offset:560
	s_waitcnt lgkmcnt(4)
	v_pk_fma_f32 v[222:223], v[22:23], v[220:221], v[222:223] op_sel:[0,1,0] op_sel_hi:[1,1,1]
	v_pk_fma_f32 v[224:225], v[24:25], v[220:221], v[224:225] op_sel:[0,1,0] op_sel_hi:[1,1,1]
	v_pk_fma_f32 v[226:227], v[26:27], v[220:221], v[226:227] op_sel:[0,1,0] op_sel_hi:[1,1,1]
	v_pk_fma_f32 v[228:229], v[28:29], v[220:221], v[228:229] op_sel:[0,1,0] op_sel_hi:[1,1,1]
	v_pk_fma_f32 v[230:231], v[30:31], v[220:221], v[230:231] op_sel:[0,1,0] op_sel_hi:[1,1,1]
	ds_read_b128 v[60:63], v175 offset:608
	ds_read_b128 v[64:67], v175 offset:624
	s_waitcnt lgkmcnt(4)
	v_fmac_f32_e32 v223, v35, v222
	v_pk_fma_f32 v[224:225], v[36:37], v[222:223], v[224:225] op_sel_hi:[1,0,1]
	v_pk_fma_f32 v[226:227], v[38:39], v[222:223], v[226:227] op_sel_hi:[1,0,1]
	v_pk_fma_f32 v[228:229], v[40:41], v[222:223], v[228:229] op_sel_hi:[1,0,1]
	v_pk_fma_f32 v[230:231], v[42:43], v[222:223], v[230:231] op_sel_hi:[1,0,1]
	ds_read_b128 v[68:71], v175 offset:672
	ds_read_b128 v[72:75], v175 offset:688
	s_waitcnt lgkmcnt(4)
	v_pk_fma_f32 v[224:225], v[44:45], v[222:223], v[224:225] op_sel:[0,1,0] op_sel_hi:[1,1,1]
	v_pk_fma_f32 v[226:227], v[46:47], v[222:223], v[226:227] op_sel:[0,1,0] op_sel_hi:[1,1,1]
	v_pk_fma_f32 v[228:229], v[48:49], v[222:223], v[228:229] op_sel:[0,1,0] op_sel_hi:[1,1,1]
	v_pk_fma_f32 v[230:231], v[50:51], v[222:223], v[230:231] op_sel:[0,1,0] op_sel_hi:[1,1,1]
	ds_read_b128 v[12:15], v175 offset:752
	s_waitcnt lgkmcnt(3)
	v_fmac_f32_e32 v225, v53, v224
	v_pk_fma_f32 v[226:227], v[54:55], v[224:225], v[226:227] op_sel_hi:[1,0,1]
	v_pk_fma_f32 v[228:229], v[56:57], v[224:225], v[228:229] op_sel_hi:[1,0,1]
	v_pk_fma_f32 v[230:231], v[58:59], v[224:225], v[230:231] op_sel_hi:[1,0,1]
	ds_read_b128 v[16:19], v175 offset:816
	s_waitcnt lgkmcnt(2)
	v_pk_fma_f32 v[226:227], v[62:63], v[224:225], v[226:227] op_sel:[0,1,0] op_sel_hi:[1,1,1]
	v_pk_fma_f32 v[228:229], v[64:65], v[224:225], v[228:229] op_sel:[0,1,0] op_sel_hi:[1,1,1]
	v_pk_fma_f32 v[230:231], v[66:67], v[224:225], v[230:231] op_sel:[0,1,0] op_sel_hi:[1,1,1]
	ds_read_b128 v[20:23], v175 offset:880
	s_waitcnt lgkmcnt(2)
	v_fmac_f32_e32 v227, v71, v226
	v_pk_fma_f32 v[228:229], v[72:73], v[226:227], v[228:229] op_sel_hi:[1,0,1]
	v_pk_fma_f32 v[230:231], v[74:75], v[226:227], v[230:231] op_sel_hi:[1,0,1]
	ds_read_b128 v[24:27], v175 offset:944
	s_waitcnt lgkmcnt(2)
	v_pk_fma_f32 v[228:229], v[12:13], v[226:227], v[228:229] op_sel:[0,1,0] op_sel_hi:[1,1,1]
	v_pk_fma_f32 v[230:231], v[14:15], v[226:227], v[230:231] op_sel:[0,1,0] op_sel_hi:[1,1,1]
	s_waitcnt lgkmcnt(1)
	v_fmac_f32_e32 v229, v17, v228
	v_pk_fma_f32 v[230:231], v[18:19], v[228:229], v[230:231] op_sel_hi:[1,0,1]
	s_waitcnt lgkmcnt(0)
	v_pk_fma_f32 v[230:231], v[22:23], v[228:229], v[230:231] op_sel:[0,1,0] op_sel_hi:[1,1,1]
	v_fmac_f32_e32 v231, v27, v230
	v_cndmask_b32_e64 v84, v220, v196, s[4:5]
	v_cndmask_b32_e64 v96, v228, v224, s[4:5]
	v_cndmask_b32_e64 v84, v96, v84, s[6:7]
	v_cndmask_b32_e64 v85, v221, v217, s[4:5]
	v_cndmask_b32_e64 v96, v229, v225, s[4:5]
	v_cndmask_b32_e64 v85, v96, v85, s[6:7]
	v_cndmask_b32_e64 v86, v222, v218, s[4:5]
	v_cndmask_b32_e64 v96, v230, v226, s[4:5]
	v_cndmask_b32_e64 v86, v96, v86, s[6:7]
	v_cndmask_b32_e64 v87, v223, v219, s[4:5]
	v_cndmask_b32_e64 v96, v231, v227, s[4:5]
	v_cndmask_b32_e64 v87, v96, v87, s[6:7]
	ds_write_b128 v91, v[84:87]
	s_branch .LBB0_915

; __device__ __forceinline__ void gn_phase(bf16_t* Y, const bf16_t* R, const bf16_t* Kb, const bf16_t* V, const bf16_t* Z, const bf16_t* WA, const float* k_a, const float* r_k, const float* gn_g, const float* gn_b, int G, int bid, int tid) {
;     const int wave = __builtin_amdgcn_readfirstlane(tid >> 6), lane = tid & 63;
;     const int gw = bid * NWAVES + wave, NGW = G * NWAVES;
;     const int col = lane * 16;
;     f32x4 kaq[4], rkq[4], ggq[4], gbq[4];
; #pragma unroll
;     for (int q = 0; q < 4; ++q) { kaq[q] = *(const f32x4*)(k_a + col + 4 * q); rkq[q] = *(const f32x4*)(r_k + col + 4 * q); ggq[q] = *(const f32x4*)(gn_g + col + 4 * q); gbq[q] = *(const f32x4*)(gn_b + col + 4 * q); }
;     u32x4 ry_[2], rr_[2], rk_[2], rv_[2], rz_[2], ra_[2];
;     ...
;     if (gw < M) GN_LOAD(gw);
.LBB0_1006:
	v_readlane_b32 s2, v254, 1
	v_readlane_b32 s3, v254, 2
	s_cmp_lt_i32 s2, 12
	s_cselect_b64 s[2:3], -1, 0
	s_and_b64 s[16:17], s[2:3], s[0:1]
	s_andn2_b64 vcc, exec, s[16:17]
	s_cbranch_vccnz .LBB0_1012
	v_mbcnt_lo_u32_b32 v64, -1, 0
	v_mbcnt_hi_u32_b32 v64, -1, v64
	s_lshl_b32 s2, s84, 3
	v_add_u32_e32 v0, s52, v64
	s_mov_b64 s[0:1], s[82:83]
	v_readfirstlane_b32 s3, v0
	s_ashr_i32 s3, s3, 6
	s_add_i32 s18, s3, s2
	s_cmpk_gt_i32 s18, 0x7fff
	s_cbranch_scc1 .LBB0_1012
	s_load_dwordx4 s[12:15], s[0:1], 0xc0
	s_lshl_b32 s20, s54, 3
	s_load_dwordx8 s[4:11], s[0:1], 0x80
	v_lshlrev_b32_e32 v0, 4, v64
	v_and_b32_e32 v160, 0x3f0, v0
	s_waitcnt lgkmcnt(0)
	s_add_u32 s22, s14, 0x4000000
	s_addc_u32 s23, s15, 0
	s_add_u32 s24, s14, 0x16000000
	s_addc_u32 s25, s15, 0
	s_add_u32 s26, s12, 0x4000000
	s_addc_u32 s27, s13, 0
	s_add_u32 s28, s14, 0x12000000
	s_addc_u32 s29, s15, 0
	s_add_u32 s0, s14, 0x8000000
	s_addc_u32 s1, s15, 0
	v_lshlrev_b32_e32 v65, 2, v160
	s_ashr_i32 s19, s18, 31
	global_load_dwordx4 v[0:3], v65, s[10:11] offset:48
	global_load_dwordx4 v[4:7], v65, s[8:9] offset:48
	global_load_dwordx4 v[8:11], v65, s[10:11] offset:32
	global_load_dwordx4 v[12:15], v65, s[8:9] offset:32
	global_load_dwordx4 v[16:19], v65, s[10:11] offset:16
	global_load_dwordx4 v[20:23], v65, s[8:9] offset:16
	global_load_dwordx4 v[24:27], v65, s[10:11]
	global_load_dwordx4 v[28:31], v65, s[8:9]
	global_load_dwordx4 v[32:35], v65, s[6:7] offset:48
	global_load_dwordx4 v[36:39], v65, s[4:5] offset:48
	global_load_dwordx4 v[40:43], v65, s[6:7] offset:32
	global_load_dwordx4 v[44:47], v65, s[4:5] offset:32
	global_load_dwordx4 v[48:51], v65, s[6:7] offset:16
	global_load_dwordx4 v[52:55], v65, s[4:5] offset:16
	s_lshl_b64 s[8:9], s[18:19], 11
	v_lshlrev_b32_e32 v66, 1, v160
	v_or_b32_e32 v56, s8, v66
	v_mov_b32_e32 v57, s9
	s_lshl_b64 s[8:9], s[18:19], 12
	s_add_u32 s8, s0, s8
	s_addc_u32 s9, s1, s9
	v_lshl_add_u64 v[68:69], s[22:23], 0, v[56:57]
	v_lshl_add_u64 v[70:71], s[24:25], 0, v[56:57]
	v_lshl_add_u64 v[72:73], s[12:13], 0, v[56:57]
	v_lshl_add_u64 v[74:75], s[26:27], 0, v[56:57]
	v_lshl_add_u64 v[76:77], s[28:29], 0, v[56:57]
	global_load_dwordx4 v[116:119], v[76:77], off offset:16
	global_load_dwordx4 v[136:139], v[76:77], off
	global_load_dwordx4 v[120:123], v[74:75], off offset:16
	global_load_dwordx4 v[144:147], v[74:75], off
	global_load_dwordx4 v[140:143], v[68:69], off offset:16
	global_load_dwordx4 v[156:159], v[68:69], off
	global_load_dwordx4 v[56:59], v65, s[6:7]
	global_load_dwordx4 v[60:63], v65, s[4:5]
	v_mbcnt_lo_u32_b32 v232, -1, 0
	v_mbcnt_hi_u32_b32 v232, -1, v232
	v_lshrrev_b32_e32 v232, 2, v232
	v_lshlrev_b32_e32 v232, 2, v232
	v_mov_b32_e32 v233, 0
	s_add_u32 s98, s14, 0x10800000
	s_addc_u32 s99, s15, 0
	v_lshl_add_u64 v[234:235], s[98:99], 0, v[232:233]
	s_lshl_b64 s[100:101], s[18:19], 6
	v_lshl_add_u64 v[236:237], v[234:235], 0, s[100:101]
	global_load_dword v238, v[236:237], off
	v_mov_b32_e32 v67, 0
	v_mbcnt_lo_u32_b32 v65, -1, 0
	v_mbcnt_hi_u32_b32 v65, -1, v65
	v_lshl_add_u64 v[162:163], s[0:1], 0, v[66:67]
	s_ashr_i32 s1, s3, 31
	s_ashr_i32 s7, s2, 31
	v_and_b32_e32 v69, 64, v65
	s_add_u32 s0, s3, s2
	v_xor_b32_e32 v68, 1, v65
	v_add_u32_e32 v69, 64, v69
	s_addc_u32 s1, s1, s7
	v_xor_b32_e32 v70, 2, v65
	v_cmp_lt_i32_e32 vcc, v68, v69
	s_lshl_b64 s[0:1], s[0:1], 11
	v_and_b32_e32 v64, 63, v64
	v_cndmask_b32_e32 v68, v65, v68, vcc
	v_cmp_lt_i32_e32 vcc, v70, v69
	s_add_u32 s0, s14, s0
	v_lshlrev_b32_e32 v66, 5, v64
	v_cndmask_b32_e32 v65, v65, v70, vcc
	s_addc_u32 s1, s15, s1
	s_mov_b64 s[4:5], 0x4000000
	v_lshlrev_b32_e32 v184, 2, v65
	v_lshl_add_u64 v[64:65], s[0:1], 0, v[66:67]
	v_lshlrev_b32_e32 v183, 2, v68
	s_ashr_i32 s21, s20, 31
	v_lshl_add_u64 v[164:165], v[64:65], 0, s[4:5]
	v_mov_b32_e32 v161, 0x3a27c5ac
	s_mov_b32 s6, 0xf800000
	v_mov_b32_e32 v182, 0x260
	s_lshl_b64 s[0:1], s[20:21], 11
	s_waitcnt vmcnt(0)
	v_mov_b32_e32 v167, v22
	v_mov_b64_e32 v[108:109], v[112:113]
	v_mov_b64_e32 v[104:105], v[128:129]
	v_mov_b64_e32 v[100:101], v[116:117]
	v_mov_b64_e32 v[96:97], v[136:137]
	v_mov_b64_e32 v[92:93], v[120:121]
	v_mov_b64_e32 v[88:89], v[144:145]
	v_mov_b64_e32 v[84:85], v[124:125]
	v_mov_b64_e32 v[80:81], v[148:149]
	v_mov_b64_e32 v[76:77], v[132:133]
	v_mov_b64_e32 v[72:73], v[152:153]
	v_mov_b64_e32 v[68:69], v[140:141]
	v_mov_b64_e32 v[64:65], v[156:157]
	v_mov_b64_e32 v[106:107], v[130:131]
	v_mov_b64_e32 v[110:111], v[114:115]
	v_mov_b64_e32 v[98:99], v[138:139]
	v_mov_b64_e32 v[102:103], v[118:119]
	v_mov_b64_e32 v[90:91], v[146:147]
	v_mov_b64_e32 v[94:95], v[122:123]
	v_mov_b64_e32 v[82:83], v[150:151]
	v_mov_b64_e32 v[86:87], v[126:127]
	v_mov_b64_e32 v[74:75], v[154:155]
	v_mov_b64_e32 v[78:79], v[134:135]
	v_mov_b64_e32 v[66:67], v[158:159]
	v_mov_b64_e32 v[70:71], v[142:143]
	s_branch .LBB0_1010
; __device__ __forceinline__ void unpack8(const u32x4 w, f32x4& a, f32x4& b) { a = (f32x4){bflo(w.x), bfhi(w.x), bflo(w.y), bfhi(w.y)}; b = (f32x4){bflo(w.z), bfhi(w.z), bflo(w.w), bfhi(w.w)}; }
; __device__ __forceinline__ void gn_phase(bf16_t* Y, const bf16_t* R, const bf16_t* Kb, const bf16_t* V, const bf16_t* Z, const bf16_t* WA, const float* k_a, const float* r_k, const float* gn_g, const float* gn_b, int G, int bid, int tid) {
;     ...
;     for (int m = gw; m < M; m += NGW) {
;         const size_t off = (size_t)m * D + col;
;         f32x4 y[4], r[4], k[4], v[4], z[4], aa[4];
; #pragma unroll
;         for (int j = 0; j < 2; ++j) { unpack8(ry_[j], y[2 * j], y[2 * j + 1]); unpack8(rr_[j], r[2 * j], r[2 * j + 1]); unpack8(rk_[j], k[2 * j], k[2 * j + 1]);
;             unpack8(rv_[j], v[2 * j], v[2 * j + 1]); unpack8(rz_[j], z[2 * j], z[2 * j + 1]); unpack8(ra_[j], aa[2 * j], aa[2 * j + 1]); }
;         if (m + NGW < M) GN_LOAD(m + NGW);
;         float s = 0.f, bs = 0.f;
; #pragma unroll
;         for (int q = 0; q < 4; ++q) {
;             s += (y[q].x + y[q].y) + (y[q].z + y[q].w);
;             const f32x4 kp = k[q] * (1.0f + (aa[q] - 1.0f) * kaq[q]);
;             const f32x4 t = r[q] * kp * rkq[q];
;             bs += (t.x + t.y) + (t.z + t.w);
;         }
;         s += __shfl_xor(s, 1); s += __shfl_xor(s, 2); bs += __shfl_xor(bs, 1); bs += __shfl_xor(bs, 2);
.LBB0_1009:
	v_lshlrev_b32_e32 v202, 16, v128
	v_and_b32_e32 v203, 0xffff0000, v128
	v_lshlrev_b32_e32 v204, 16, v129
	v_and_b32_e32 v205, 0xffff0000, v129
	v_pk_add_f32 v[204:205], v[204:205], -1.0 op_sel_hi:[1,0]
	v_pk_add_f32 v[202:203], v[202:203], -1.0 op_sel_hi:[1,0]
	v_lshlrev_b32_e32 v194, 16, v148
	v_and_b32_e32 v195, 0xffff0000, v148
	v_lshlrev_b32_e32 v196, 16, v149
	v_and_b32_e32 v197, 0xffff0000, v149
	v_pk_fma_f32 v[202:203], v[60:61], v[202:203], 1.0 op_sel_hi:[1,1,0]
	v_pk_fma_f32 v[204:205], v[62:63], v[204:205], 1.0 op_sel_hi:[1,1,0]
	v_lshlrev_b32_e32 v186, 16, v152
	v_and_b32_e32 v187, 0xffff0000, v152
	v_lshlrev_b32_e32 v188, 16, v153
	v_and_b32_e32 v189, 0xffff0000, v153
	v_pk_mul_f32 v[196:197], v[204:205], v[196:197]
	v_pk_mul_f32 v[194:195], v[202:203], v[194:195]
	v_pk_mul_f32 v[188:189], v[196:197], v[188:189]
	v_pk_mul_f32 v[186:187], v[194:195], v[186:187]
	v_pk_mul_f32 v[188:189], v[58:59], v[188:189]
	v_pk_mul_f32 v[186:187], v[56:57], v[186:187]
	v_lshlrev_b32_e32 v206, 16, v130
	v_and_b32_e32 v207, 0xffff0000, v130
	v_lshlrev_b32_e32 v208, 16, v131
	v_and_b32_e32 v209, 0xffff0000, v131
	v_pk_mov_b32 v[194:195], v[186:187], v[188:189] op_sel:[1,0]
	v_mov_b32_e32 v187, v189
	v_pk_add_f32 v[186:187], v[194:195], v[186:187]
	v_pk_add_f32 v[194:195], v[208:209], -1.0 op_sel_hi:[1,0]
	v_pk_add_f32 v[196:197], v[206:207], -1.0 op_sel_hi:[1,0]
	v_lshlrev_b32_e32 v177, 16, v157
	v_lshlrev_b32_e32 v176, 16, v156
	v_and_b32_e32 v175, 0xffff0000, v157
	v_and_b32_e32 v174, 0xffff0000, v156
	v_lshlrev_b32_e32 v169, 16, v159
	v_lshlrev_b32_e32 v168, 16, v158
	v_and_b32_e32 v157, 0xffff0000, v159
	v_and_b32_e32 v156, 0xffff0000, v158
	v_lshlrev_b32_e32 v198, 16, v150
	v_and_b32_e32 v199, 0xffff0000, v150
	v_lshlrev_b32_e32 v200, 16, v151
	v_and_b32_e32 v201, 0xffff0000, v151
	v_pk_fma_f32 v[196:197], v[52:53], v[196:197], 1.0 op_sel_hi:[1,1,0]
	v_pk_fma_f32 v[194:195], v[54:55], v[194:195], 1.0 op_sel_hi:[1,1,0]
	v_lshlrev_b32_e32 v190, 16, v154
	v_and_b32_e32 v191, 0xffff0000, v154
	v_lshlrev_b32_e32 v192, 16, v155
	v_and_b32_e32 v193, 0xffff0000, v155
	v_pk_add_f32 v[224:225], v[176:177], v[174:175]
	v_pk_add_f32 v[188:189], v[168:169], v[156:157]
	v_pk_mul_f32 v[194:195], v[194:195], v[200:201]
	v_pk_mul_f32 v[196:197], v[196:197], v[198:199]
	v_lshlrev_b32_e32 v172, 16, v144
	v_and_b32_e32 v170, 0xffff0000, v144
	v_lshlrev_b32_e32 v158, 16, v145
	v_and_b32_e32 v154, 0xffff0000, v145
	v_lshlrev_b32_e32 v144, 16, v140
	v_and_b32_e32 v145, 0xffff0000, v140
	v_lshlrev_b32_e32 v140, 16, v141
	v_and_b32_e32 v141, 0xffff0000, v141
	v_add_f32_e32 v129, v224, v225
	v_add_f32_e32 v131, v186, v187
	v_pk_add_f32 v[188:189], v[188:189], v[188:189] op_sel_hi:[0,1]
	v_pk_mul_f32 v[190:191], v[196:197], v[190:191]
	v_pk_mul_f32 v[192:193], v[194:195], v[192:193]
	v_lshlrev_b32_e32 v152, 16, v146
	v_and_b32_e32 v150, 0xffff0000, v146
	v_lshlrev_b32_e32 v166, 16, v147
	v_and_b32_e32 v146, 0xffff0000, v147
	v_lshlrev_b32_e32 v147, 16, v136
	v_and_b32_e32 v149, 0xffff0000, v136
	v_lshlrev_b32_e32 v185, 16, v137
	v_and_b32_e32 v226, 0xffff0000, v137
	v_lshlrev_b32_e32 v227, 16, v138
	v_and_b32_e32 v228, 0xffff0000, v138
	v_lshlrev_b32_e32 v229, 16, v139
	v_and_b32_e32 v230, 0xffff0000, v139
	v_lshlrev_b32_e32 v138, 16, v142
	v_and_b32_e32 v136, 0xffff0000, v142
	v_lshlrev_b32_e32 v130, 16, v143
	v_and_b32_e32 v128, 0xffff0000, v143
	v_add_f32_e32 v129, 0, v129
	v_add_f32_e32 v187, 0, v131
	v_pk_mul_f32 v[192:193], v[50:51], v[192:193]
	v_pk_mul_f32 v[190:191], v[48:49], v[190:191]
	v_add_f32_e32 v139, v144, v145
	v_add_f32_e32 v137, v140, v141
	v_mov_b32_e32 v131, v189
	v_pk_mov_b32 v[194:195], v[190:191], v[192:193] op_sel:[1,0]
	v_mov_b32_e32 v191, v193
	v_pk_add_f32 v[192:193], v[138:139], v[136:137]
	v_pk_add_f32 v[188:189], v[130:131], v[128:129]
	v_lshlrev_b32_e32 v210, 16, v132
	v_pk_add_f32 v[188:189], v[192:193], v[188:189]
	v_and_b32_e32 v211, 0xffff0000, v132
	v_lshlrev_b32_e32 v212, 16, v133
	v_and_b32_e32 v213, 0xffff0000, v133
	v_lshlrev_b32_e32 v178, 16, v134
	v_and_b32_e32 v179, 0xffff0000, v134
	v_lshlrev_b32_e32 v214, 16, v124
	v_and_b32_e32 v215, 0xffff0000, v124
	v_lshlrev_b32_e32 v216, 16, v125
	v_and_b32_e32 v217, 0xffff0000, v125
	v_lshlrev_b32_e32 v218, 16, v126
	v_and_b32_e32 v219, 0xffff0000, v126
	v_lshlrev_b32_e32 v220, 16, v127
	v_and_b32_e32 v221, 0xffff0000, v127
	v_lshlrev_b32_e32 v148, 16, v120
	v_and_b32_e32 v142, 0xffff0000, v120
	v_lshlrev_b32_e32 v134, 16, v121
	v_and_b32_e32 v132, 0xffff0000, v121
	v_lshlrev_b32_e32 v126, 16, v122
	v_and_b32_e32 v124, 0xffff0000, v122
	v_lshlrev_b32_e32 v122, 16, v123
	v_and_b32_e32 v120, 0xffff0000, v123
	v_lshlrev_b32_e32 v127, 16, v116
	v_and_b32_e32 v133, 0xffff0000, v116
	v_lshlrev_b32_e32 v125, 16, v117
	v_and_b32_e32 v123, 0xffff0000, v117
	v_lshlrev_b32_e32 v121, 16, v118
	v_and_b32_e32 v117, 0xffff0000, v118
	v_lshlrev_b32_e32 v116, 16, v119
	v_and_b32_e32 v22, 0xffff0000, v119
	v_lshlrev_b32_e32 v118, 16, v112
	v_and_b32_e32 v119, 0xffff0000, v112
	v_lshlrev_b32_e32 v112, 16, v113
	v_and_b32_e32 v113, 0xffff0000, v113
	v_add_f32_e32 v129, v188, v189
	v_pk_add_f32 v[112:113], v[112:113], -1.0 op_sel_hi:[1,0]
	ds_bpermute_b32 v131, v183, v129
	v_pk_add_f32 v[118:119], v[118:119], -1.0 op_sel_hi:[1,0]
	v_pk_fma_f32 v[112:113], v[46:47], v[112:113], 1.0 op_sel_hi:[1,1,0]
	v_pk_fma_f32 v[118:119], v[44:45], v[118:119], 1.0 op_sel_hi:[1,1,0]
	v_pk_mul_f32 v[112:113], v[112:113], v[216:217]
	v_pk_mul_f32 v[118:119], v[118:119], v[214:215]
	v_pk_mul_f32 v[112:113], v[112:113], v[212:213]
	v_pk_mul_f32 v[118:119], v[118:119], v[210:211]
	v_pk_mul_f32 v[112:113], v[42:43], v[112:113]
	v_pk_mul_f32 v[118:119], v[40:41], v[118:119]
	v_add_f32_e32 v113, v112, v113
	s_waitcnt lgkmcnt(0)
; __device__ __forceinline__ float fsigmoid(float x) { return __builtin_amdgcn_rcpf(1.0f + __expf(-x)); }
; __device__ __forceinline__ void gn_phase(bf16_t* Y, const bf16_t* R, const bf16_t* Kb, const bf16_t* V, const bf16_t* Z, const bf16_t* WA, const float* k_a, const float* r_k, const float* gn_g, const float* gn_b, int G, int bid, int tid) {
;     ...
;         s += __shfl_xor(s, 1); s += __shfl_xor(s, 2); bs += __shfl_xor(bs, 1); bs += __shfl_xor(bs, 2);
;         const float mean = s * (1.0f / 64.0f);
;         float q2 = 0.f;
; #pragma unroll
;         for (int q = 0; q < 4; ++q) { const f32x4 dlt = y[q] - mean; q2 += (dlt.x * dlt.x + dlt.y * dlt.y) + (dlt.z * dlt.z + dlt.w * dlt.w); }
;         q2 += __shfl_xor(q2, 1); q2 += __shfl_xor(q2, 2);
;         const float rstd = 1.0f / sqrtf(q2 * (1.0f / 64.0f) + 64e-5f);
;         f32x4 o[4];
; #pragma unroll
;         for (int q = 0; q < 4; ++q) {
;             const f32x4 yn = (y[q] - mean) * rstd * ggq[q] + gbq[q] + bs * v[q];
; #pragma unroll
;             for (int e = 0; e < 4; ++e) o[q][e] = yn[e] * z[q][e] * fsigmoid(z[q][e]);
	v_add_f32_e32 v112, v129, v131
	v_add_f32_e32 v119, v118, v119
	ds_bpermute_b32 v118, v184, v112
	v_pk_add_f32 v[190:191], v[194:195], v[190:191]
	v_lshlrev_b32_e32 v222, 16, v114
	v_and_b32_e32 v223, 0xffff0000, v114
	v_lshlrev_b32_e32 v114, 16, v115
	s_waitcnt lgkmcnt(0)
	v_add_f32_e32 v129, v112, v118
	v_fmac_f32_e32 v174, 0xbc800000, v129
	v_fmac_f32_e32 v175, 0xbc800000, v129
	v_fmac_f32_e32 v177, 0xbc800000, v129
	v_fmac_f32_e32 v176, 0xbc800000, v129
	v_mov_b32_e32 v192, v177
	v_mov_b32_e32 v193, v175
	v_mov_b32_e32 v194, v176
	v_mov_b32_e32 v195, v174
	v_pk_mul_f32 v[192:193], v[192:193], v[192:193]
	v_pk_mul_f32 v[194:195], v[194:195], v[194:195]
	v_fmac_f32_e32 v156, 0xbc800000, v129
	v_pk_mov_b32 v[196:197], v[194:195], v[192:193] op_sel:[1,0]
	v_mov_b32_e32 v195, v193
	v_pk_add_f32 v[192:193], v[196:197], v[194:195]
	v_fmac_f32_e32 v157, 0xbc800000, v129
	v_mov_b32_e32 v196, v168
	v_fmamk_f32 v194, v129, 0xbc800000, v169
	v_mov_b32_e32 v195, v157
	v_fmac_f32_e32 v196, 0xbc800000, v129
	v_mov_b32_e32 v197, v156
	v_pk_mul_f32 v[194:195], v[194:195], v[194:195]
	v_pk_mul_f32 v[198:199], v[196:197], v[196:197]
	v_fmac_f32_e32 v144, 0xbc800000, v129
	v_pk_mov_b32 v[200:201], v[198:199], v[194:195] op_sel:[1,0]
	v_mov_b32_e32 v199, v195
	v_fmac_f32_e32 v140, 0xbc800000, v129
	v_fmac_f32_e32 v145, 0xbc800000, v129
	v_mul_f32_e32 v112, v144, v144
	v_pk_add_f32 v[194:195], v[200:201], v[198:199]
	v_fmac_f32_e32 v141, 0xbc800000, v129
	v_pk_fma_f32 v[198:199], v[144:145], v[144:145], v[112:113] op_sel_hi:[1,1,0]
	v_mul_f32_e32 v112, v140, v140
	v_pk_add_f32 v[192:193], v[192:193], v[192:193] op_sel_hi:[0,1]
	v_pk_add_f32 v[194:195], v[194:195], v[194:195] op_sel_hi:[0,1]
	v_pk_fma_f32 v[200:201], v[140:141], v[140:141], v[112:113] op_sel_hi:[1,1,0]
	v_fmac_f32_e32 v138, 0xbc800000, v129
	v_fmac_f32_e32 v136, 0xbc800000, v129
	v_fmac_f32_e32 v130, 0xbc800000, v129
	v_fmac_f32_e32 v128, 0xbc800000, v129
	v_mul_f32_e32 v198, v138, v138
	v_mul_f32_e32 v200, v136, v136
	v_mul_f32_e32 v192, v130, v130
	v_mul_f32_e32 v194, v128, v128
	v_pk_add_f32 v[198:199], v[198:199], v[200:201]
	v_pk_add_f32 v[192:193], v[192:193], v[194:195]
	v_and_b32_e32 v115, 0xffff0000, v115
	v_pk_add_f32 v[192:193], v[198:199], v[192:193]
	v_lshlrev_b32_e32 v180, 16, v135
	v_add_f32_e32 v112, v192, v193
	ds_bpermute_b32 v118, v183, v112
	v_and_b32_e32 v181, 0xffff0000, v135
	v_pk_add_f32 v[114:115], v[114:115], -1.0 op_sel_hi:[1,0]
	v_pk_add_f32 v[188:189], v[222:223], -1.0 op_sel_hi:[1,0]
	v_pk_fma_f32 v[114:115], v[38:39], v[114:115], 1.0 op_sel_hi:[1,1,0]
	s_waitcnt lgkmcnt(0)
	v_add_f32_e32 v131, v112, v118
	ds_bpermute_b32 v135, v184, v131
	v_pk_fma_f32 v[188:189], v[36:37], v[188:189], 1.0 op_sel_hi:[1,1,0]
	v_pk_mul_f32 v[114:115], v[114:115], v[220:221]
	v_pk_mul_f32 v[188:189], v[188:189], v[218:219]
	v_pk_mul_f32 v[114:115], v[114:115], v[180:181]
	v_pk_add_f32 v[190:191], v[190:191], v[190:191] op_sel_hi:[0,1]
	v_pk_mul_f32 v[178:179], v[188:189], v[178:179]
	v_pk_mul_f32 v[114:115], v[34:35], v[114:115]
	v_pk_mul_f32 v[178:179], v[32:33], v[178:179]
	v_mov_b32_e32 v190, v114
	s_waitcnt lgkmcnt(0)
	v_add_f32_e32 v114, v131, v135
	v_mov_b32_e32 v118, v178
	v_mov_b32_e32 v112, v179
	v_fmamk_f32 v114, v114, 0x3c800000, v161
	v_pk_add_f32 v[112:113], v[118:119], v[112:113]
	v_mul_f32_e32 v118, 0x4f800000, v114
	v_cmp_gt_f32_e32 vcc, s6, v114
	v_mov_b32_e32 v186, v115
	s_nop 0
	v_cndmask_b32_e32 v118, v114, v118, vcc
	v_sqrt_f32_e32 v119, v118
	v_pk_add_f32 v[114:115], v[190:191], v[186:187]
	s_nop 0
	v_pk_add_f32 v[112:113], v[112:113], v[114:115]
	v_add_u32_e32 v114, -1, v119
	v_fma_f32 v115, -v114, v119, v118
	v_cmp_ge_f32_e64 s[2:3], 0, v115
	v_add_u32_e32 v115, 1, v119
	s_nop 0
	v_cndmask_b32_e64 v114, v119, v114, s[2:3]
	v_fma_f32 v119, -v115, v119, v118
	v_cmp_lt_f32_e64 s[2:3], 0, v119
	s_nop 1
	v_cndmask_b32_e64 v114, v114, v115, s[2:3]
	v_mul_f32_e32 v115, 0x37800000, v114
	v_cndmask_b32_e32 v114, v114, v115, vcc
	v_cmp_class_f32_e32 vcc, v118, v182
	s_nop 1
	v_cndmask_b32_e32 v119, v114, v118, vcc
	v_div_scale_f32 v131, s[2:3], v119, v119, 1.0
	v_rcp_f32_e32 v135, v131
	v_pk_add_f32 v[114:115], v[112:113], v[112:113] op_sel:[0,1] op_sel_hi:[1,0]
	ds_bpermute_b32 v118, v183, v114
	v_mul_f32_e32 v115, 0x3c800000, v129
	v_fma_f32 v112, -v131, v135, 1.0
	v_fmac_f32_e32 v135, v112, v135
	v_div_scale_f32 v112, vcc, 1.0, v119, 1.0
	v_mul_f32_e32 v113, v112, v135
	v_fma_f32 v129, -v131, v113, v112
	v_fmac_f32_e32 v113, v129, v135
	v_mul_f32_e32 v129, 0xbfb8aa3b, v147
	v_exp_f32_e32 v129, v129
	v_fma_f32 v112, -v131, v113, v112
	v_div_fmas_f32 v112, v112, v135, v113
	v_div_fixup_f32 v113, v112, v119, 1.0
	v_add_f32_e32 v112, 1.0, v129
	v_rcp_f32_e32 v129, v112
	v_mul_f32_e32 v112, 0xbfb8aa3b, v149
	v_exp_f32_e32 v112, v112
	v_mul_f32_e32 v119, 0xbfb8aa3b, v185
	v_exp_f32_e32 v119, v119
	v_mul_f32_e32 v173, v176, v113
	v_add_f32_e32 v112, 1.0, v112
	v_rcp_f32_e32 v131, v112
	v_add_f32_e32 v112, 1.0, v119
	v_rcp_f32_e32 v135, v112
	v_mul_f32_e32 v112, 0xbfb8aa3b, v226
	v_exp_f32_e32 v112, v112
	v_mul_f32_e32 v119, 0xbfb8aa3b, v227
	v_exp_f32_e32 v119, v119
	v_mul_f32_e32 v171, v174, v113
	v_add_f32_e32 v112, 1.0, v112
	v_rcp_f32_e32 v137, v112
	v_add_f32_e32 v112, 1.0, v119
	v_mov_b32_e32 v119, v169
	v_rcp_f32_e32 v139, v112
	v_mul_f32_e32 v112, 0xbfb8aa3b, v228
	s_waitcnt lgkmcnt(0)
	v_pk_add_f32 v[118:119], v[114:115], v[118:119]
	v_exp_f32_e32 v143, v112
	ds_bpermute_b32 v112, v184, v118
	v_pk_add_f32 v[168:169], v[168:169], v[114:115] neg_lo:[0,1] neg_hi:[0,1]
	v_mul_f32_e32 v159, v177, v113
	v_mul_f32_e32 v155, v175, v113
	v_mul_f32_e32 v151, v156, v113
	s_waitcnt lgkmcnt(0)
; __device__ __forceinline__ float fsigmoid(float x) { return __builtin_amdgcn_rcpf(1.0f + __expf(-x)); }
; __device__ __forceinline__ u32x4 pack8(const f32x4 a, const f32x4 b) { u32x4 w; w.x = cvt_pk_bf16(a[0], a[1]); w.y = cvt_pk_bf16(a[2], a[3]); w.z = cvt_pk_bf16(b[0], b[1]); w.w = cvt_pk_bf16(b[2], b[3]); return w; }
; __device__ __forceinline__ void gn_phase(bf16_t* Y, const bf16_t* R, const bf16_t* Kb, const bf16_t* V, const bf16_t* Z, const bf16_t* WA, const float* k_a, const float* r_k, const float* gn_g, const float* gn_b, int G, int bid, int tid) {
;     ...
;         f32x4 o[4];
; #pragma unroll
;         for (int q = 0; q < 4; ++q) {
;             const f32x4 yn = (y[q] - mean) * rstd * ggq[q] + gbq[q] + bs * v[q];
; #pragma unroll
;             for (int e = 0; e < 4; ++e) o[q][e] = yn[e] * z[q][e] * fsigmoid(z[q][e]);
;         }
;         *(u32x4*)(Y + off) = pack8(o[0], o[1]); *(u32x4*)(Y + off + 8) = pack8(o[2], o[3]);
	v_pk_add_f32 v[114:115], v[118:119], v[112:113]
	v_mov_b32_e32 v114, v238
	v_pk_mul_f32 v[118:119], v[168:169], v[112:113]
	v_mul_f32_e32 v153, v196, v113
	v_mov_b32_e32 v115, v119
	v_mov_b32_e32 v118, v114
	v_mov_b32_e32 v119, v28
	v_pk_mul_f32 v[118:119], v[118:119], v[172:173]
	v_add_f32_e32 v143, 1.0, v143
	v_add_f32_e32 v112, v24, v119
	v_add_f32_e32 v112, v118, v112
	v_mov_b32_e32 v118, v114
	v_mov_b32_e32 v119, v29
	v_mul_f32_e32 v112, v112, v147
	v_pk_mul_f32 v[118:119], v[118:119], v[170:171]
	v_mul_f32_e32 v129, v129, v112
	v_add_f32_e32 v112, v25, v119
	v_add_f32_e32 v112, v118, v112
	v_mov_b32_e32 v118, v114
	v_mov_b32_e32 v119, v30
	v_mul_f32_e32 v112, v112, v149
	v_pk_mul_f32 v[118:119], v[118:119], v[158:159]
	v_mul_f32_e32 v131, v131, v112
	v_add_f32_e32 v112, v26, v119
	v_add_f32_e32 v112, v118, v112
	v_mov_b32_e32 v118, v114
	v_mov_b32_e32 v119, v31
	v_mul_f32_e32 v112, v112, v185
	v_pk_mul_f32 v[118:119], v[118:119], v[154:155]
	v_mul_f32_e32 v156, v135, v112
	v_add_f32_e32 v112, v27, v119
	v_add_f32_e32 v112, v118, v112
	v_mov_b32_e32 v118, v114
	v_mov_b32_e32 v119, v20
	v_mul_f32_e32 v112, v112, v226
	v_pk_mul_f32 v[118:119], v[118:119], v[152:153]
	v_mul_f32_e32 v137, v137, v112
	v_add_f32_e32 v112, v16, v119
	v_add_f32_e32 v112, v118, v112
	v_mov_b32_e32 v118, v114
	v_mov_b32_e32 v119, v21
	v_mul_f32_e32 v112, v112, v227
	v_pk_mul_f32 v[118:119], v[118:119], v[150:151]
	v_mul_f32_e32 v139, v139, v112
	v_add_f32_e32 v112, v17, v119
	v_add_f32_e32 v112, v118, v112
	v_mul_f32_e32 v118, 0xbfb8aa3b, v229
	v_rcp_f32_e32 v143, v143
	v_exp_f32_e32 v135, v118
	v_mul_f32_e32 v112, v112, v228
	v_pk_mul_f32 v[118:119], v[114:115], v[166:167]
	v_mul_f32_e32 v150, v143, v112
	v_add_f32_e32 v112, 1.0, v135
	v_rcp_f32_e32 v112, v112
	v_add_f32_e32 v115, v18, v119
	v_add_f32_e32 v115, v118, v115
	v_mul_f32_e32 v115, v115, v229
	v_mul_f32_e32 v151, v112, v115
	v_mul_f32_e32 v112, 0xbfb8aa3b, v230
	v_exp_f32_e32 v112, v112
	v_mul_f32_e32 v147, v157, v113
	v_mov_b32_e32 v115, v23
	v_pk_mul_f32 v[118:119], v[114:115], v[146:147]
	v_add_f32_e32 v112, 1.0, v112
	v_rcp_f32_e32 v112, v112
	v_add_f32_e32 v115, v19, v119
	v_add_f32_e32 v115, v118, v115
	v_mul_f32_e32 v115, v115, v230
	v_mul_f32_e32 v146, v112, v115
	v_mul_f32_e32 v112, 0xbfb8aa3b, v127
	v_exp_f32_e32 v112, v112
	v_mul_f32_e32 v149, v144, v113
	v_mov_b32_e32 v115, v12
	v_pk_mul_f32 v[118:119], v[114:115], v[148:149]
	v_add_f32_e32 v112, 1.0, v112
	v_rcp_f32_e32 v112, v112
	v_add_f32_e32 v115, v8, v119
	v_add_f32_e32 v115, v118, v115
	v_mul_f32_e32 v115, v115, v127
	v_mul_f32_e32 v144, v112, v115
	v_mul_f32_e32 v112, 0xbfb8aa3b, v133
	v_exp_f32_e32 v112, v112
	v_mul_f32_e32 v143, v145, v113
	v_mov_b32_e32 v115, v13
	v_pk_mul_f32 v[118:119], v[114:115], v[142:143]
	v_add_f32_e32 v112, 1.0, v112
	v_rcp_f32_e32 v112, v112
	v_add_f32_e32 v115, v9, v119
	v_add_f32_e32 v115, v118, v115
	v_mul_f32_e32 v115, v115, v133
	v_mul_f32_e32 v142, v112, v115
	v_mul_f32_e32 v112, 0xbfb8aa3b, v125
	v_exp_f32_e32 v112, v112
	v_mul_f32_e32 v135, v140, v113
	v_mov_b32_e32 v115, v14
	v_pk_mul_f32 v[118:119], v[114:115], v[134:135]
	v_add_f32_e32 v112, 1.0, v112
	v_rcp_f32_e32 v112, v112
	v_add_f32_e32 v115, v10, v119
	v_add_f32_e32 v115, v118, v115
	v_mul_f32_e32 v115, v115, v125
	v_mul_f32_e32 v134, v112, v115
	v_mul_f32_e32 v112, 0xbfb8aa3b, v123
	v_exp_f32_e32 v112, v112
	v_mul_f32_e32 v133, v141, v113
	v_mov_b32_e32 v115, v15
	v_pk_mul_f32 v[118:119], v[114:115], v[132:133]
	v_add_f32_e32 v112, 1.0, v112
	v_rcp_f32_e32 v112, v112
	v_add_f32_e32 v115, v11, v119
	v_add_f32_e32 v115, v118, v115
	v_mul_f32_e32 v115, v115, v123
	v_mul_f32_e32 v132, v112, v115
	v_mul_f32_e32 v112, 0xbfb8aa3b, v121
	v_exp_f32_e32 v112, v112
	v_mul_f32_e32 v127, v138, v113
	v_mov_b32_e32 v115, v4
	v_pk_mul_f32 v[118:119], v[114:115], v[126:127]
	v_add_f32_e32 v112, 1.0, v112
	v_rcp_f32_e32 v112, v112
	v_add_f32_e32 v115, v0, v119
	v_add_f32_e32 v115, v118, v115
	v_mul_f32_e32 v115, v115, v121
	v_mul_f32_e32 v126, v112, v115
	v_mul_f32_e32 v112, 0xbfb8aa3b, v117
	v_exp_f32_e32 v112, v112
	v_mul_f32_e32 v125, v136, v113
	v_mov_b32_e32 v115, v5
	v_pk_mul_f32 v[118:119], v[114:115], v[124:125]
	v_add_f32_e32 v112, 1.0, v112
	v_rcp_f32_e32 v112, v112
	v_add_f32_e32 v115, v1, v119
	v_add_f32_e32 v115, v118, v115
	v_mul_f32_e32 v115, v115, v117
	v_mul_f32_e32 v117, v112, v115
	v_mul_f32_e32 v112, 0xbfb8aa3b, v116
	v_exp_f32_e32 v112, v112
	v_mul_f32_e32 v123, v130, v113
	v_mov_b32_e32 v115, v6
	v_pk_mul_f32 v[118:119], v[114:115], v[122:123]
	v_add_f32_e32 v112, 1.0, v112
	v_rcp_f32_e32 v112, v112
	v_add_f32_e32 v115, v2, v119
	v_add_f32_e32 v115, v118, v115
	v_mul_f32_e32 v115, v115, v116
	v_mul_f32_e32 v116, v112, v115
	v_mul_f32_e32 v112, 0xbfb8aa3b, v22
	v_exp_f32_e32 v118, v112
	v_mul_f32_e32 v121, v128, v113
	v_mov_b32_e32 v115, v7
	v_pk_mul_f32 v[112:113], v[114:115], v[120:121]
	v_add_f32_e32 v114, 1.0, v118
	v_rcp_f32_e32 v114, v114
	v_add_f32_e32 v113, v3, v113
	v_add_f32_e32 v112, v112, v113
	v_mul_f32_e32 v22, v112, v22
	v_mul_f32_e32 v22, v114, v22
	v_cvt_pk_bf16_f32 v112, v129, v131
	v_cvt_pk_bf16_f32 v113, v156, v137
	v_cvt_pk_bf16_f32 v114, v139, v150
	v_cvt_pk_bf16_f32 v115, v151, v146
	global_store_dwordx4 v[164:165], v[112:115], off
	s_waitcnt vmcnt(1)
	v_mov_b64_e32 v[130:131], v[106:107]
	v_mov_b64_e32 v[138:139], v[98:99]
	v_cvt_pk_bf16_f32 v112, v144, v142
	v_cvt_pk_bf16_f32 v113, v134, v132
	v_cvt_pk_bf16_f32 v114, v126, v117
	v_cvt_pk_bf16_f32 v115, v116, v22
	global_store_dwordx4 v[164:165], v[112:115], off offset:16
	v_mov_b64_e32 v[118:119], v[102:103]
	v_mov_b64_e32 v[146:147], v[90:91]
	v_mov_b64_e32 v[114:115], v[110:111]
	v_mov_b64_e32 v[122:123], v[94:95]
	v_mov_b64_e32 v[150:151], v[82:83]
	v_mov_b64_e32 v[126:127], v[86:87]
	v_mov_b64_e32 v[154:155], v[74:75]
	v_mov_b64_e32 v[134:135], v[78:79]
	v_mov_b64_e32 v[158:159], v[66:67]
	v_mov_b64_e32 v[142:143], v[70:71]
	v_lshl_add_u64 v[164:165], v[164:165], 0, s[0:1]
	s_andn2_b64 vcc, exec, s[4:5]
	v_mov_b64_e32 v[128:129], v[104:105]
	v_mov_b64_e32 v[112:113], v[108:109]
	v_mov_b64_e32 v[136:137], v[96:97]
	v_mov_b64_e32 v[116:117], v[100:101]
	v_mov_b64_e32 v[144:145], v[88:89]
	v_mov_b64_e32 v[120:121], v[92:93]
	v_mov_b64_e32 v[148:149], v[80:81]
	v_mov_b64_e32 v[124:125], v[84:85]
	v_mov_b64_e32 v[152:153], v[72:73]
	v_mov_b64_e32 v[132:133], v[76:77]
	v_mov_b64_e32 v[156:157], v[64:65]
	v_mov_b64_e32 v[140:141], v[68:69]
	v_mov_b32_e32 v238, v239
	s_cbranch_vccz .LBB0_1012
; __device__ __forceinline__ void unpack8(const u32x4 w, f32x4& a, f32x4& b) { a = (f32x4){bflo(w.x), bfhi(w.x), bflo(w.y), bfhi(w.y)}; b = (f32x4){bflo(w.z), bfhi(w.z), bflo(w.w), bfhi(w.w)}; }
; __device__ __forceinline__ void gn_phase(bf16_t* Y, const bf16_t* R, const bf16_t* Kb, const bf16_t* V, const bf16_t* Z, const bf16_t* WA, const float* k_a, const float* r_k, const float* gn_g, const float* gn_b, int G, int bid, int tid) {
;     ...
;     if (gw < M) GN_LOAD(gw);
;     for (int m = gw; m < M; m += NGW) {
;         const size_t off = (size_t)m * D + col;
;         f32x4 y[4], r[4], k[4], v[4], z[4], aa[4];
; #pragma unroll
;         for (int j = 0; j < 2; ++j) { unpack8(ry_[j], y[2 * j], y[2 * j + 1]); unpack8(rr_[j], r[2 * j], r[2 * j + 1]); unpack8(rk_[j], k[2 * j], k[2 * j + 1]);
;             unpack8(rv_[j], v[2 * j], v[2 * j + 1]); unpack8(rz_[j], z[2 * j], z[2 * j + 1]); unpack8(ra_[j], aa[2 * j], aa[2 * j + 1]); }
;         if (m + NGW < M) GN_LOAD(m + NGW);
.LBB0_1010:
	s_add_i32 s18, s18, s20
	s_cmpk_gt_i32 s18, 0x7fff
	s_cselect_b64 s[4:5], -1, 0
	s_and_b64 vcc, exec, s[4:5]
	s_cbranch_vccnz .LBB0_1009
	s_ashr_i32 s19, s18, 31
	s_lshl_b64 s[100:101], s[18:19], 6
	v_lshl_add_u64 v[236:237], v[234:235], 0, s[100:101]
	global_load_dword v239, v[236:237], off
	s_lshl_b64 s[2:3], s[18:19], 11
	v_lshl_or_b32 v64, v160, 1, s2
	v_mov_b32_e32 v65, s3
	s_lshl_b64 s[2:3], s[18:19], 12
	v_lshl_add_u64 v[66:67], s[22:23], 0, v[64:65]
	v_lshl_add_u64 v[72:73], s[24:25], 0, v[64:65]
	v_lshl_add_u64 v[80:81], s[12:13], 0, v[64:65]
	v_lshl_add_u64 v[88:89], s[26:27], 0, v[64:65]
	v_lshl_add_u64 v[96:97], s[28:29], 0, v[64:65]
	v_lshl_add_u64 v[104:105], v[162:163], 0, s[2:3]
	global_load_dwordx4 v[68:71], v[66:67], off offset:16
	s_nop 0
	global_load_dwordx4 v[64:67], v[66:67], off
	s_nop 0
	s_nop 0
	s_nop 0
	s_nop 0
	s_nop 0
	global_load_dwordx4 v[92:95], v[88:89], off offset:16
	s_nop 0
	global_load_dwordx4 v[88:91], v[88:89], off
	s_nop 0
	global_load_dwordx4 v[100:103], v[96:97], off offset:16
	s_nop 0
	global_load_dwordx4 v[96:99], v[96:97], off
	s_nop 0
	s_nop 0
	s_branch .LBB0_1009

; __global__ void __launch_bounds__(NTHR, 2) hybrid_fwd(Args a) {
	.amdhsa_kernel _Z10hybrid_fwd4Args
		.amdhsa_group_segment_fixed_size 0
		.amdhsa_private_segment_fixed_size 0
		.amdhsa_kernarg_size 472
		.amdhsa_user_sgpr_count 2
		.amdhsa_user_sgpr_dispatch_ptr 0
		.amdhsa_user_sgpr_queue_ptr 0
		.amdhsa_user_sgpr_kernarg_segment_ptr 1
		.amdhsa_user_sgpr_dispatch_id 0
		.amdhsa_user_sgpr_kernarg_preload_length 0
		.amdhsa_user_sgpr_kernarg_preload_offset 0
		.amdhsa_user_sgpr_private_segment_size 0
		.amdhsa_uses_dynamic_stack 0
		.amdhsa_enable_private_segment 0
		.amdhsa_system_sgpr_workgroup_id_x 1
		.amdhsa_system_sgpr_workgroup_id_y 0
		.amdhsa_system_sgpr_workgroup_id_z 0
		.amdhsa_system_sgpr_workgroup_info 0
		.amdhsa_system_vgpr_workitem_id 2
		.amdhsa_next_free_vgpr 255
		.amdhsa_next_free_sgpr 102
		.amdhsa_accum_offset 256
		.amdhsa_reserve_vcc 1
		.amdhsa_float_round_mode_32 0
		.amdhsa_float_round_mode_16_64 0
		.amdhsa_float_denorm_mode_32 3
		.amdhsa_float_denorm_mode_16_64 3
		.amdhsa_dx10_clamp 1
		.amdhsa_ieee_mode 1
		.amdhsa_fp16_overflow 0
		.amdhsa_tg_split 0
		.amdhsa_exception_fp_ieee_invalid_op 0
		.amdhsa_exception_fp_denorm_src 0
		.amdhsa_exception_fp_ieee_div_zero 0
		.amdhsa_exception_fp_ieee_overflow 0
		.amdhsa_exception_fp_ieee_underflow 0
		.amdhsa_exception_fp_ieee_inexact 0
		.amdhsa_exception_int_div_zero 0
	.end_amdhsa_kernel

; __global__ void __launch_bounds__(NTHR, 2) hybrid_fwd(Args a) {
amdhsa.kernels:
  - .agpr_count:     0
    .args:
      - .offset:         0
        .size:           216
        .value_kind:     by_value
      - .offset:         216
        .size:           4
        .value_kind:     hidden_block_count_x
      - .offset:         220
        .size:           4
        .value_kind:     hidden_block_count_y
      - .offset:         224
        .size:           4
        .value_kind:     hidden_block_count_z
      - .offset:         228
        .size:           2
        .value_kind:     hidden_group_size_x
      - .offset:         230
        .size:           2
        .value_kind:     hidden_group_size_y
      - .offset:         232
        .size:           2
        .value_kind:     hidden_group_size_z
      - .offset:         234
        .size:           2
        .value_kind:     hidden_remainder_x
      - .offset:         236
        .size:           2
        .value_kind:     hidden_remainder_y
      - .offset:         238
        .size:           2
        .value_kind:     hidden_remainder_z
      - .offset:         256
        .size:           8
        .value_kind:     hidden_global_offset_x
      - .offset:         264
        .size:           8
        .value_kind:     hidden_global_offset_y
      - .offset:         272
        .size:           8
        .value_kind:     hidden_global_offset_z
      - .offset:         280
        .size:           2
        .value_kind:     hidden_grid_dims
      - .offset:         304
        .size:           8
        .value_kind:     hidden_multigrid_sync_arg
      - .offset:         336
        .size:           4
        .value_kind:     hidden_dynamic_lds_size
    .group_segment_fixed_size: 0
    .kernarg_segment_align: 8
    .kernarg_segment_size: 472
    .language:       OpenCL C
    .language_version:
      - 2
      - 0
    .max_flat_workgroup_size: 512
    .name:           _Z10hybrid_fwd4Args
    .private_segment_fixed_size: 0
    .sgpr_count:     108
    .sgpr_spill_count: 13
    .symbol:         _Z10hybrid_fwd4Args.kd
    .uniform_work_group_size: 1
    .uses_dynamic_stack: false
    .vgpr_count:     255
    .vgpr_spill_count: 0
    .wavefront_size: 64
